# all six GEMM loops: per-phase s_setprio flips deleted (96 instructions)
# speedup vs baseline: 1.0071x; 1.0009x over previous
.LBB0_58:
	s_add_u32 s44, s42, 0x100
	s_addc_u32 s45, s43, 0
	s_add_i32 s23, 0, 0x10000
	v_add_u32_e32 v145, s23, v143
	ds_read_b128 v[146:149], v145
	ds_read_b128 v[150:153], v145 offset:1024
	ds_read_b128 v[154:157], v145 offset:2048
	ds_read_b128 v[158:161], v145 offset:3072
	s_cmp_eq_u32 s22, 40
	s_cselect_b32 s49, s1, s45
	s_cselect_b32 s48, s0, s44
	s_cselect_b32 s47, s41, s21
	s_cselect_b32 s46, s40, s20
	v_lshl_add_u64 v[194:195], s[42:43], 0, v[138:139]
	s_add_i32 m0, s52, 0xc000
	ds_read_b128 v[162:165], v144
	ds_read_b128 v[166:169], v144 offset:1024
	ds_read_b128 v[170:173], v144 offset:2048
	ds_read_b128 v[174:177], v144 offset:3072
	ds_read_b128 v[178:181], v144 offset:4096
	ds_read_b128 v[182:185], v144 offset:5120
	ds_read_b128 v[186:189], v144 offset:6144
	ds_read_b128 v[190:193], v144 offset:7168
	global_load_lds_dwordx4 v[194:195], off
	v_lshl_add_u64 v[194:195], s[42:43], 0, v[140:141]
	s_add_i32 m0, s52, 0xe000
	s_nop 0
	global_load_lds_dwordx4 v[194:195], off
	s_waitcnt lgkmcnt(8)
	s_barrier
	s_waitcnt lgkmcnt(0)
	s_waitcnt lgkmcnt(0)
	v_mfma_f32_16x16x32_bf16 v[128:131], v[146:149], v[162:165], v[128:131]
	v_mfma_f32_16x16x32_bf16 v[124:127], v[154:157], v[162:165], v[124:127]
	v_mfma_f32_16x16x32_bf16 v[120:123], v[146:149], v[170:173], v[120:123]
	v_mfma_f32_16x16x32_bf16 v[116:119], v[154:157], v[170:173], v[116:119]
	v_mfma_f32_16x16x32_bf16 v[104:107], v[146:149], v[178:181], v[104:107]
	v_mfma_f32_16x16x32_bf16 v[100:103], v[154:157], v[178:181], v[100:103]
	v_mfma_f32_16x16x32_bf16 v[88:91], v[146:149], v[186:189], v[88:91]
	v_mfma_f32_16x16x32_bf16 v[84:87], v[154:157], v[186:189], v[84:87]
	v_mfma_f32_16x16x32_bf16 v[128:131], v[150:153], v[166:169], v[128:131]
	v_mfma_f32_16x16x32_bf16 v[124:127], v[158:161], v[166:169], v[124:127]
	v_mfma_f32_16x16x32_bf16 v[120:123], v[150:153], v[174:177], v[120:123]
	v_mfma_f32_16x16x32_bf16 v[116:119], v[158:161], v[174:177], v[116:119]
	v_mfma_f32_16x16x32_bf16 v[104:107], v[150:153], v[182:185], v[104:107]
	v_mfma_f32_16x16x32_bf16 v[100:103], v[158:161], v[182:185], v[100:103]
	v_mfma_f32_16x16x32_bf16 v[88:91], v[150:153], v[190:193], v[88:91]
	v_mfma_f32_16x16x32_bf16 v[84:87], v[158:161], v[190:193], v[84:87]
	s_barrier
	s_add_i32 s26, 0, 0x14000
	s_add_i32 s23, s23, s37
	v_add_u32_e32 v145, s26, v143
	v_lshl_add_u64 v[194:195], s[46:47], 0, v[132:133]
	s_mov_b32 m0, s23
	ds_read_b128 v[202:205], v145
	ds_read_b128 v[206:209], v145 offset:1024
	ds_read_b128 v[210:213], v145 offset:2048
	ds_read_b128 v[214:217], v145 offset:3072
	global_load_lds_dwordx4 v[194:195], off
	v_lshl_add_u64 v[198:199], s[46:47], 0, v[136:137]
	s_add_i32 m0, s23, 0x2000
	s_nop 0
	global_load_lds_dwordx4 v[198:199], off
	s_barrier
	s_waitcnt lgkmcnt(0)
	s_waitcnt lgkmcnt(0)
	v_mfma_f32_16x16x32_bf16 v[112:115], v[202:205], v[162:165], v[112:115]
	v_mfma_f32_16x16x32_bf16 v[108:111], v[210:213], v[162:165], v[108:111]
	v_mfma_f32_16x16x32_bf16 v[96:99], v[202:205], v[170:173], v[96:99]
	v_mfma_f32_16x16x32_bf16 v[92:95], v[210:213], v[170:173], v[92:95]
	v_mfma_f32_16x16x32_bf16 v[80:83], v[202:205], v[178:181], v[80:83]
	v_mfma_f32_16x16x32_bf16 v[76:79], v[210:213], v[178:181], v[76:79]
	v_mfma_f32_16x16x32_bf16 v[72:75], v[202:205], v[186:189], v[72:75]
	v_mfma_f32_16x16x32_bf16 v[68:71], v[210:213], v[186:189], v[68:71]
	v_mfma_f32_16x16x32_bf16 v[112:115], v[206:209], v[166:169], v[112:115]
	v_mfma_f32_16x16x32_bf16 v[108:111], v[214:217], v[166:169], v[108:111]
	v_mfma_f32_16x16x32_bf16 v[96:99], v[206:209], v[174:177], v[96:99]
	v_mfma_f32_16x16x32_bf16 v[92:95], v[214:217], v[174:177], v[92:95]
	v_mfma_f32_16x16x32_bf16 v[80:83], v[206:209], v[182:185], v[80:83]
	v_mfma_f32_16x16x32_bf16 v[76:79], v[214:217], v[182:185], v[76:79]
	v_mfma_f32_16x16x32_bf16 v[72:75], v[206:209], v[190:193], v[72:75]
	v_mfma_f32_16x16x32_bf16 v[68:71], v[214:217], v[190:193], v[68:71]
	s_mov_b32 m0, s52
	v_lshl_add_u64 v[222:223], s[48:49], 0, v[0:1]
	s_barrier
	ds_read_b128 v[162:165], v144 offset:16384
	ds_read_b128 v[166:169], v144 offset:17408
	ds_read_b128 v[170:173], v144 offset:18432
	ds_read_b128 v[174:177], v144 offset:19456
	ds_read_b128 v[178:181], v144 offset:20480
	ds_read_b128 v[182:185], v144 offset:21504
	ds_read_b128 v[186:189], v144 offset:22528
	ds_read_b128 v[190:193], v144 offset:23552
	global_load_lds_dwordx4 v[222:223], off
	v_lshl_add_u64 v[236:237], s[48:49], 0, v[134:135]
	s_mov_b32 m0, s53
	s_nop 0
	global_load_lds_dwordx4 v[236:237], off
	s_barrier
	s_waitcnt lgkmcnt(0)
	s_waitcnt lgkmcnt(0)
	v_mfma_f32_16x16x32_bf16 v[64:67], v[146:149], v[162:165], v[64:67]
	v_mfma_f32_16x16x32_bf16 v[60:63], v[154:157], v[162:165], v[60:63]
	v_mfma_f32_16x16x32_bf16 v[56:59], v[146:149], v[170:173], v[56:59]
	v_mfma_f32_16x16x32_bf16 v[52:55], v[154:157], v[170:173], v[52:55]
	v_mfma_f32_16x16x32_bf16 v[40:43], v[146:149], v[178:181], v[40:43]
	v_mfma_f32_16x16x32_bf16 v[36:39], v[154:157], v[178:181], v[36:39]
	v_mfma_f32_16x16x32_bf16 v[24:27], v[146:149], v[186:189], v[24:27]
	v_mfma_f32_16x16x32_bf16 v[16:19], v[154:157], v[186:189], v[16:19]
	v_mfma_f32_16x16x32_bf16 v[64:67], v[150:153], v[166:169], v[64:67]
	v_mfma_f32_16x16x32_bf16 v[60:63], v[158:161], v[166:169], v[60:63]
	v_mfma_f32_16x16x32_bf16 v[56:59], v[150:153], v[174:177], v[56:59]
	v_mfma_f32_16x16x32_bf16 v[52:55], v[158:161], v[174:177], v[52:55]
	v_mfma_f32_16x16x32_bf16 v[40:43], v[150:153], v[182:185], v[40:43]
	v_mfma_f32_16x16x32_bf16 v[36:39], v[158:161], v[182:185], v[36:39]
	v_mfma_f32_16x16x32_bf16 v[24:27], v[150:153], v[190:193], v[24:27]
	v_mfma_f32_16x16x32_bf16 v[16:19], v[158:161], v[190:193], v[16:19]
	s_barrier
	s_add_u32 s24, s46, 0xb0000
	s_addc_u32 s25, s47, 0
	s_add_i32 s23, s26, s37
	v_lshl_add_u64 v[146:147], s[24:25], 0, v[132:133]
	s_mov_b32 m0, s23
	s_nop 0
	global_load_lds_dwordx4 v[146:147], off
	v_lshl_add_u64 v[146:147], s[24:25], 0, v[136:137]
	s_add_i32 m0, s23, 0x2000
	s_nop 0
	global_load_lds_dwordx4 v[146:147], off
	s_waitcnt vmcnt(6)
	s_barrier
	v_mfma_f32_16x16x32_bf16 v[48:51], v[202:205], v[162:165], v[48:51]
	v_mfma_f32_16x16x32_bf16 v[44:47], v[210:213], v[162:165], v[44:47]
	v_mfma_f32_16x16x32_bf16 v[32:35], v[202:205], v[170:173], v[32:35]
	v_mfma_f32_16x16x32_bf16 v[28:31], v[210:213], v[170:173], v[28:31]
	v_mfma_f32_16x16x32_bf16 v[20:23], v[202:205], v[178:181], v[20:23]
	v_mfma_f32_16x16x32_bf16 v[12:15], v[210:213], v[178:181], v[12:15]
	v_mfma_f32_16x16x32_bf16 v[8:11], v[202:205], v[186:189], v[8:11]
	v_mfma_f32_16x16x32_bf16 v[4:7], v[210:213], v[186:189], v[4:7]
	v_mfma_f32_16x16x32_bf16 v[48:51], v[206:209], v[166:169], v[48:51]
	v_mfma_f32_16x16x32_bf16 v[44:47], v[214:217], v[166:169], v[44:47]
	v_mfma_f32_16x16x32_bf16 v[32:35], v[206:209], v[174:177], v[32:35]
	v_mfma_f32_16x16x32_bf16 v[28:31], v[214:217], v[174:177], v[28:31]
	v_mfma_f32_16x16x32_bf16 v[20:23], v[206:209], v[182:185], v[20:23]
	v_mfma_f32_16x16x32_bf16 v[12:15], v[214:217], v[182:185], v[12:15]
	v_mfma_f32_16x16x32_bf16 v[8:11], v[206:209], v[190:193], v[8:11]
	v_mfma_f32_16x16x32_bf16 v[4:7], v[214:217], v[190:193], v[4:7]
	s_add_i32 s23, 0, 0x18000
	v_add_u32_e32 v145, s23, v143
	s_barrier
	ds_read_b128 v[146:149], v145
	ds_read_b128 v[150:153], v145 offset:1024
	ds_read_b128 v[154:157], v145 offset:2048
	ds_read_b128 v[158:161], v145 offset:3072
	s_add_u32 s24, s48, 0xb0000
	s_addc_u32 s25, s49, 0
	s_mov_b32 m0, s54
	v_lshl_add_u64 v[202:203], s[24:25], 0, v[0:1]
	ds_read_b128 v[162:165], v144 offset:32768
	ds_read_b128 v[166:169], v144 offset:33792
	ds_read_b128 v[170:173], v144 offset:34816
	ds_read_b128 v[174:177], v144 offset:35840
	ds_read_b128 v[178:181], v144 offset:36864
	ds_read_b128 v[182:185], v144 offset:37888
	ds_read_b128 v[186:189], v144 offset:38912
	ds_read_b128 v[190:193], v144 offset:39936
	global_load_lds_dwordx4 v[202:203], off
	v_lshl_add_u64 v[202:203], s[24:25], 0, v[134:135]
	s_mov_b32 m0, s55
	s_nop 0
	global_load_lds_dwordx4 v[202:203], off
	s_waitcnt lgkmcnt(8)
	s_barrier
	s_waitcnt lgkmcnt(0)
	s_waitcnt lgkmcnt(0)
	v_mfma_f32_16x16x32_bf16 v[128:131], v[146:149], v[162:165], v[128:131]
	v_mfma_f32_16x16x32_bf16 v[124:127], v[154:157], v[162:165], v[124:127]
	v_mfma_f32_16x16x32_bf16 v[120:123], v[146:149], v[170:173], v[120:123]
	v_mfma_f32_16x16x32_bf16 v[116:119], v[154:157], v[170:173], v[116:119]
	v_mfma_f32_16x16x32_bf16 v[104:107], v[146:149], v[178:181], v[104:107]
	v_mfma_f32_16x16x32_bf16 v[100:103], v[154:157], v[178:181], v[100:103]
	v_mfma_f32_16x16x32_bf16 v[88:91], v[146:149], v[186:189], v[88:91]
	v_mfma_f32_16x16x32_bf16 v[84:87], v[154:157], v[186:189], v[84:87]
	v_mfma_f32_16x16x32_bf16 v[128:131], v[150:153], v[166:169], v[128:131]
	v_mfma_f32_16x16x32_bf16 v[124:127], v[158:161], v[166:169], v[124:127]
	v_mfma_f32_16x16x32_bf16 v[120:123], v[150:153], v[174:177], v[120:123]
	v_mfma_f32_16x16x32_bf16 v[116:119], v[158:161], v[174:177], v[116:119]
	v_mfma_f32_16x16x32_bf16 v[104:107], v[150:153], v[182:185], v[104:107]
	v_mfma_f32_16x16x32_bf16 v[100:103], v[158:161], v[182:185], v[100:103]
	v_mfma_f32_16x16x32_bf16 v[88:91], v[150:153], v[190:193], v[88:91]
	v_mfma_f32_16x16x32_bf16 v[84:87], v[158:161], v[190:193], v[84:87]
	s_barrier
	s_add_i32 s26, 0, 0x1c000
	s_add_i32 s23, s23, s37
	v_add_u32_e32 v145, s26, v143
	v_lshl_add_u64 v[194:195], v[194:195], 0, s[76:77]
	s_mov_b32 m0, s23
	ds_read_b128 v[202:205], v145
	ds_read_b128 v[206:209], v145 offset:1024
	ds_read_b128 v[210:213], v145 offset:2048
	ds_read_b128 v[214:217], v145 offset:3072
	global_load_lds_dwordx4 v[194:195], off
	v_lshl_add_u64 v[194:195], v[198:199], 0, s[76:77]
	s_add_i32 m0, s23, 0x2000
	s_nop 0
	global_load_lds_dwordx4 v[194:195], off
	s_barrier
	s_waitcnt lgkmcnt(0)
	s_waitcnt lgkmcnt(0)
	v_mfma_f32_16x16x32_bf16 v[112:115], v[202:205], v[162:165], v[112:115]
	v_mfma_f32_16x16x32_bf16 v[108:111], v[210:213], v[162:165], v[108:111]
	v_mfma_f32_16x16x32_bf16 v[96:99], v[202:205], v[170:173], v[96:99]
	v_mfma_f32_16x16x32_bf16 v[92:95], v[210:213], v[170:173], v[92:95]
	v_mfma_f32_16x16x32_bf16 v[80:83], v[202:205], v[178:181], v[80:83]
	v_mfma_f32_16x16x32_bf16 v[76:79], v[210:213], v[178:181], v[76:79]
	v_mfma_f32_16x16x32_bf16 v[72:75], v[202:205], v[186:189], v[72:75]
	v_mfma_f32_16x16x32_bf16 v[68:71], v[210:213], v[186:189], v[68:71]
	v_mfma_f32_16x16x32_bf16 v[112:115], v[206:209], v[166:169], v[112:115]
	v_mfma_f32_16x16x32_bf16 v[108:111], v[214:217], v[166:169], v[108:111]
	v_mfma_f32_16x16x32_bf16 v[96:99], v[206:209], v[174:177], v[96:99]
	v_mfma_f32_16x16x32_bf16 v[92:95], v[214:217], v[174:177], v[92:95]
	v_mfma_f32_16x16x32_bf16 v[80:83], v[206:209], v[182:185], v[80:83]
	v_mfma_f32_16x16x32_bf16 v[76:79], v[214:217], v[182:185], v[76:79]
	v_mfma_f32_16x16x32_bf16 v[72:75], v[206:209], v[190:193], v[72:75]
	v_mfma_f32_16x16x32_bf16 v[68:71], v[214:217], v[190:193], v[68:71]
	s_mov_b32 m0, s56
	v_lshl_add_u64 v[194:195], v[222:223], 0, s[76:77]
	s_barrier
	ds_read_b128 v[162:165], v144 offset:49152
	ds_read_b128 v[166:169], v144 offset:50176
	ds_read_b128 v[170:173], v144 offset:51200
	ds_read_b128 v[174:177], v144 offset:52224
	ds_read_b128 v[178:181], v144 offset:53248
	ds_read_b128 v[182:185], v144 offset:54272
	ds_read_b128 v[186:189], v144 offset:55296
	ds_read_b128 v[190:193], v144 offset:56320
	global_load_lds_dwordx4 v[194:195], off
	v_lshl_add_u64 v[194:195], v[236:237], 0, s[76:77]
	s_mov_b32 m0, s57
	s_nop 0
	global_load_lds_dwordx4 v[194:195], off
	s_barrier
	s_waitcnt lgkmcnt(0)
	s_waitcnt lgkmcnt(0)
	v_mfma_f32_16x16x32_bf16 v[64:67], v[146:149], v[162:165], v[64:67]
	v_mfma_f32_16x16x32_bf16 v[60:63], v[154:157], v[162:165], v[60:63]
	v_mfma_f32_16x16x32_bf16 v[56:59], v[146:149], v[170:173], v[56:59]
	v_mfma_f32_16x16x32_bf16 v[52:55], v[154:157], v[170:173], v[52:55]
	v_mfma_f32_16x16x32_bf16 v[40:43], v[146:149], v[178:181], v[40:43]
	v_mfma_f32_16x16x32_bf16 v[36:39], v[154:157], v[178:181], v[36:39]
	v_mfma_f32_16x16x32_bf16 v[24:27], v[146:149], v[186:189], v[24:27]
	v_mfma_f32_16x16x32_bf16 v[16:19], v[154:157], v[186:189], v[16:19]
	v_mfma_f32_16x16x32_bf16 v[64:67], v[150:153], v[166:169], v[64:67]
	v_mfma_f32_16x16x32_bf16 v[60:63], v[158:161], v[166:169], v[60:63]
	v_mfma_f32_16x16x32_bf16 v[56:59], v[150:153], v[174:177], v[56:59]
	v_mfma_f32_16x16x32_bf16 v[52:55], v[158:161], v[174:177], v[52:55]
	v_mfma_f32_16x16x32_bf16 v[40:43], v[150:153], v[182:185], v[40:43]
	v_mfma_f32_16x16x32_bf16 v[36:39], v[158:161], v[182:185], v[36:39]
	v_mfma_f32_16x16x32_bf16 v[24:27], v[150:153], v[190:193], v[24:27]
	v_mfma_f32_16x16x32_bf16 v[16:19], v[158:161], v[190:193], v[16:19]
	s_barrier
	s_add_u32 s24, s46, 0xb0080
	s_addc_u32 s25, s47, 0
	s_add_i32 s23, s26, s37
	v_lshl_add_u64 v[146:147], s[24:25], 0, v[132:133]
	s_mov_b32 m0, s23
	s_nop 0
	global_load_lds_dwordx4 v[146:147], off
	v_lshl_add_u64 v[146:147], s[24:25], 0, v[136:137]
	s_add_i32 m0, s23, 0x2000
	s_nop 0
	global_load_lds_dwordx4 v[146:147], off
	s_waitcnt vmcnt(6)
	s_barrier
	v_mfma_f32_16x16x32_bf16 v[48:51], v[202:205], v[162:165], v[48:51]
	v_mfma_f32_16x16x32_bf16 v[44:47], v[210:213], v[162:165], v[44:47]
	v_mfma_f32_16x16x32_bf16 v[32:35], v[202:205], v[170:173], v[32:35]
	v_mfma_f32_16x16x32_bf16 v[28:31], v[210:213], v[170:173], v[28:31]
	v_mfma_f32_16x16x32_bf16 v[20:23], v[202:205], v[178:181], v[20:23]
	v_mfma_f32_16x16x32_bf16 v[12:15], v[210:213], v[178:181], v[12:15]
	v_mfma_f32_16x16x32_bf16 v[8:11], v[202:205], v[186:189], v[8:11]
	v_mfma_f32_16x16x32_bf16 v[4:7], v[210:213], v[186:189], v[4:7]
	v_mfma_f32_16x16x32_bf16 v[48:51], v[206:209], v[166:169], v[48:51]
	v_mfma_f32_16x16x32_bf16 v[44:47], v[214:217], v[166:169], v[44:47]
	v_mfma_f32_16x16x32_bf16 v[32:35], v[206:209], v[174:177], v[32:35]
	v_mfma_f32_16x16x32_bf16 v[28:31], v[214:217], v[174:177], v[28:31]
	v_mfma_f32_16x16x32_bf16 v[20:23], v[206:209], v[182:185], v[20:23]
	v_mfma_f32_16x16x32_bf16 v[12:15], v[214:217], v[182:185], v[12:15]
	v_mfma_f32_16x16x32_bf16 v[8:11], v[206:209], v[190:193], v[8:11]
	v_mfma_f32_16x16x32_bf16 v[4:7], v[214:217], v[190:193], v[4:7]
	s_add_i32 s22, s22, 2
	s_add_u32 s20, s20, 0x100
	s_addc_u32 s21, s21, 0
	s_cmp_gt_u32 s22, 41
	s_mov_b64 s[42:43], s[44:45]
	s_barrier
	s_cbranch_scc0 .LBB0_58
	v_lshl_add_u32 v146, s61, 8, v142
	v_cvt_pk_bf16_f32 v72, v72, v73
	v_cvt_pk_bf16_f32 v73, v74, v75
	v_cvt_pk_bf16_f32 v74, v68, v69
	v_add_u32_e32 v68, 0x80, v146
	s_lshl_b32 s20, s62, 8
	v_ashrrev_i32_e32 v147, 31, v146
	v_readlane_b32 s22, v252, 10
	v_cvt_pk_bf16_f32 v112, v112, v113
	v_cvt_pk_bf16_f32 v113, v114, v115
	v_cvt_pk_bf16_f32 v114, v108, v109
	v_or_b32_e32 v108, 16, v146
	v_ashrrev_i32_e32 v69, 31, v68
	v_cvt_pk_bf16_f32 v48, v48, v49
	v_cvt_pk_bf16_f32 v49, v50, v51
	v_cvt_pk_bf16_f32 v50, v44, v45
	v_add_u32_e32 v44, 0x90, v146
	s_ashr_i32 s21, s20, 31
	v_lshlrev_b64 v[148:149], 11, v[146:147]
	v_readlane_b32 s23, v252, 11
	v_ashrrev_i32_e32 v109, 31, v108
	v_cvt_pk_bf16_f32 v96, v96, v97
	v_cvt_pk_bf16_f32 v97, v98, v99
	v_cvt_pk_bf16_f32 v98, v92, v93
	v_or_b32_e32 v92, 32, v146
	v_lshlrev_b64 v[68:69], 11, v[68:69]
	v_ashrrev_i32_e32 v45, 31, v44
	v_cvt_pk_bf16_f32 v32, v32, v33
	v_cvt_pk_bf16_f32 v33, v34, v35
	v_cvt_pk_bf16_f32 v34, v28, v29
	v_add_u32_e32 v28, 0xa0, v146
	v_lshl_add_u64 v[148:149], s[22:23], 0, v[148:149]
	s_lshl_b64 s[42:43], s[20:21], 1
	v_lshlrev_b64 v[108:109], 11, v[108:109]
	v_ashrrev_i32_e32 v93, 31, v92
	v_cvt_pk_bf16_f32 v80, v80, v81
	v_cvt_pk_bf16_f32 v81, v82, v83
	v_cvt_pk_bf16_f32 v82, v76, v77
	v_or_b32_e32 v76, 48, v146
	v_lshl_add_u64 v[68:69], s[22:23], 0, v[68:69]
	v_lshlrev_b64 v[44:45], 11, v[44:45]
	v_ashrrev_i32_e32 v29, 31, v28
	v_cvt_pk_bf16_f32 v20, v20, v21
	v_cvt_pk_bf16_f32 v21, v22, v23
	v_cvt_pk_bf16_f32 v22, v12, v13
	v_add_u32_e32 v12, 0xb0, v146
	v_lshl_add_u64 v[148:149], v[148:149], 0, s[42:43]
	v_lshl_add_u64 v[108:109], s[22:23], 0, v[108:109]
	v_lshlrev_b64 v[92:93], 11, v[92:93]
	v_ashrrev_i32_e32 v77, 31, v76
	v_lshl_add_u64 v[68:69], v[68:69], 0, s[42:43]
	v_lshl_add_u64 v[44:45], s[22:23], 0, v[44:45]
	v_lshlrev_b64 v[28:29], 11, v[28:29]
	v_ashrrev_i32_e32 v13, 31, v12
	v_lshl_add_u64 v[148:149], v[148:149], 0, s[72:73]
	v_lshl_add_u64 v[108:109], v[108:109], 0, s[42:43]
	v_lshl_add_u64 v[92:93], s[22:23], 0, v[92:93]
	v_lshlrev_b64 v[76:77], 11, v[76:77]
	v_lshl_add_u64 v[68:69], v[68:69], 0, s[72:73]
	v_lshl_add_u64 v[44:45], v[44:45], 0, s[42:43]
	v_lshl_add_u64 v[28:29], s[22:23], 0, v[28:29]
	v_lshlrev_b64 v[12:13], 11, v[12:13]
	v_lshl_add_u64 v[148:149], v[148:149], 0, v[2:3]
	v_cvt_pk_bf16_f32 v115, v110, v111
	v_lshl_add_u64 v[108:109], v[108:109], 0, s[72:73]
	v_lshl_add_u64 v[92:93], v[92:93], 0, s[42:43]
	v_lshl_add_u64 v[76:77], s[22:23], 0, v[76:77]
	v_lshl_add_u64 v[68:69], v[68:69], 0, v[2:3]
	v_cvt_pk_bf16_f32 v51, v46, v47
	v_lshl_add_u64 v[44:45], v[44:45], 0, s[72:73]
	v_lshl_add_u64 v[28:29], v[28:29], 0, s[42:43]
	v_lshl_add_u64 v[12:13], s[22:23], 0, v[12:13]
	global_store_dwordx4 v[148:149], v[112:115], off offset:256
	v_cvt_pk_bf16_f32 v99, v94, v95
	v_lshl_add_u64 v[92:93], v[92:93], 0, s[72:73]
	v_lshl_add_u64 v[112:113], v[108:109], 0, v[2:3]
	v_lshl_add_u64 v[76:77], v[76:77], 0, s[42:43]
	global_store_dwordx4 v[68:69], v[48:51], off offset:256
	v_cvt_pk_bf16_f32 v35, v30, v31
	v_lshl_add_u64 v[28:29], v[28:29], 0, s[72:73]
	v_lshl_add_u64 v[48:49], v[44:45], 0, v[2:3]
	v_lshl_add_u64 v[12:13], v[12:13], 0, s[42:43]
	global_store_dwordx4 v[112:113], v[96:99], off offset:256
	v_cvt_pk_bf16_f32 v83, v78, v79
	v_lshl_add_u64 v[76:77], v[76:77], 0, s[72:73]
	v_lshl_add_u64 v[96:97], v[92:93], 0, v[2:3]
	global_store_dwordx4 v[48:49], v[32:35], off offset:256
	v_cvt_pk_bf16_f32 v23, v14, v15
	v_lshl_add_u64 v[12:13], v[12:13], 0, s[72:73]
	v_lshl_add_u64 v[32:33], v[28:29], 0, v[2:3]
	v_cvt_pk_bf16_f32 v128, v128, v129
	v_cvt_pk_bf16_f32 v129, v130, v131
	v_cvt_pk_bf16_f32 v130, v124, v125
	v_cvt_pk_bf16_f32 v131, v126, v127
	v_cvt_pk_bf16_f32 v108, v120, v121
	v_cvt_pk_bf16_f32 v109, v122, v123
	v_cvt_pk_bf16_f32 v110, v116, v117
	v_cvt_pk_bf16_f32 v111, v118, v119
	v_cvt_pk_bf16_f32 v92, v104, v105
	v_cvt_pk_bf16_f32 v93, v106, v107
	v_cvt_pk_bf16_f32 v94, v100, v101
	v_cvt_pk_bf16_f32 v95, v102, v103
	global_store_dwordx4 v[96:97], v[80:83], off offset:256
	v_cvt_pk_bf16_f32 v78, v84, v85
	v_cvt_pk_bf16_f32 v79, v86, v87
	v_lshl_add_u64 v[80:81], v[76:77], 0, v[2:3]
	v_cvt_pk_bf16_f32 v76, v88, v89
	v_cvt_pk_bf16_f32 v77, v90, v91
	v_cvt_pk_bf16_f32 v75, v70, v71
	v_cvt_pk_bf16_f32 v64, v64, v65
	v_cvt_pk_bf16_f32 v65, v66, v67
	v_cvt_pk_bf16_f32 v66, v60, v61
	v_cvt_pk_bf16_f32 v67, v62, v63
	v_cvt_pk_bf16_f32 v44, v56, v57
	v_cvt_pk_bf16_f32 v45, v58, v59
	v_cvt_pk_bf16_f32 v46, v52, v53
	v_cvt_pk_bf16_f32 v47, v54, v55
	v_cvt_pk_bf16_f32 v28, v40, v41
	v_cvt_pk_bf16_f32 v29, v42, v43
	v_cvt_pk_bf16_f32 v30, v36, v37
	v_cvt_pk_bf16_f32 v31, v38, v39
	global_store_dwordx4 v[32:33], v[20:23], off offset:256
	v_cvt_pk_bf16_f32 v14, v16, v17
	v_cvt_pk_bf16_f32 v15, v18, v19
	v_lshl_add_u64 v[20:21], v[12:13], 0, v[2:3]
	v_cvt_pk_bf16_f32 v12, v24, v25
	v_cvt_pk_bf16_f32 v13, v26, v27
	v_cvt_pk_bf16_f32 v8, v8, v9
	v_cvt_pk_bf16_f32 v9, v10, v11
	v_cvt_pk_bf16_f32 v10, v4, v5
	v_cvt_pk_bf16_f32 v11, v6, v7
	s_and_b64 vcc, exec, s[38:39]
	s_mov_b32 s62, s59
	s_mov_b32 s61, s60
	s_mov_b64 s[44:45], s[40:41]
	s_mov_b64 s[42:43], s[0:1]
	global_store_dwordx4 v[148:149], v[128:131], off
	global_store_dwordx4 v[112:113], v[108:111], off
	global_store_dwordx4 v[96:97], v[92:95], off
	global_store_dwordx4 v[80:81], v[76:79], off
	global_store_dwordx4 v[80:81], v[72:75], off offset:256
	global_store_dwordx4 v[68:69], v[64:67], off
	global_store_dwordx4 v[48:49], v[44:47], off
	global_store_dwordx4 v[32:33], v[28:31], off
	global_store_dwordx4 v[20:21], v[12:15], off
	global_store_dwordx4 v[20:21], v[8:11], off offset:256
	s_cbranch_vccz .LBB0_51
	s_waitcnt vmcnt(0)
	s_cmpk_gt_u32 s36, 0xff
	s_cbranch_scc1 .LBB0_62
	s_barrier

.LBB0_136:
	s_add_u32 s23, s48, 0xfffc0080
	s_addc_u32 s24, s49, -1
	s_add_i32 s25, 0, 0x10000
	v_add_u32_e32 v145, s25, v143
	ds_read_b128 v[146:149], v145
	ds_read_b128 v[150:153], v145 offset:1024
	ds_read_b128 v[154:157], v145 offset:2048
	ds_read_b128 v[158:161], v145 offset:3072
	s_cmp_eq_u32 s22, 12
	s_cselect_b32 s53, s45, s24
	s_cselect_b32 s52, s44, s23
	s_cselect_b32 s51, s47, s21
	s_cselect_b32 s50, s46, s20
	v_lshl_add_u64 v[194:195], s[48:49], 0, v[138:139]
	s_add_i32 m0, s54, 0xc000
	ds_read_b128 v[162:165], v144
	ds_read_b128 v[166:169], v144 offset:1024
	ds_read_b128 v[170:173], v144 offset:2048
	ds_read_b128 v[174:177], v144 offset:3072
	ds_read_b128 v[178:181], v144 offset:4096
	ds_read_b128 v[182:185], v144 offset:5120
	ds_read_b128 v[186:189], v144 offset:6144
	ds_read_b128 v[190:193], v144 offset:7168
	global_load_lds_dwordx4 v[194:195], off
	v_lshl_add_u64 v[194:195], s[48:49], 0, v[140:141]
	s_add_i32 m0, s54, 0xe000
	s_nop 0
	global_load_lds_dwordx4 v[194:195], off
	s_waitcnt lgkmcnt(8)
	s_barrier
	s_waitcnt lgkmcnt(0)
	s_waitcnt lgkmcnt(0)
	v_mfma_f32_16x16x32_bf16 v[128:131], v[146:149], v[162:165], v[128:131]
	v_mfma_f32_16x16x32_bf16 v[124:127], v[154:157], v[162:165], v[124:127]
	v_mfma_f32_16x16x32_bf16 v[120:123], v[146:149], v[170:173], v[120:123]
	v_mfma_f32_16x16x32_bf16 v[116:119], v[154:157], v[170:173], v[116:119]
	v_mfma_f32_16x16x32_bf16 v[104:107], v[146:149], v[178:181], v[104:107]
	v_mfma_f32_16x16x32_bf16 v[100:103], v[154:157], v[178:181], v[100:103]
	v_mfma_f32_16x16x32_bf16 v[88:91], v[146:149], v[186:189], v[88:91]
	v_mfma_f32_16x16x32_bf16 v[84:87], v[154:157], v[186:189], v[84:87]
	v_mfma_f32_16x16x32_bf16 v[128:131], v[150:153], v[166:169], v[128:131]
	v_mfma_f32_16x16x32_bf16 v[124:127], v[158:161], v[166:169], v[124:127]
	v_mfma_f32_16x16x32_bf16 v[120:123], v[150:153], v[174:177], v[120:123]
	v_mfma_f32_16x16x32_bf16 v[116:119], v[158:161], v[174:177], v[116:119]
	v_mfma_f32_16x16x32_bf16 v[104:107], v[150:153], v[182:185], v[104:107]
	v_mfma_f32_16x16x32_bf16 v[100:103], v[158:161], v[182:185], v[100:103]
	v_mfma_f32_16x16x32_bf16 v[88:91], v[150:153], v[190:193], v[88:91]
	v_mfma_f32_16x16x32_bf16 v[84:87], v[158:161], v[190:193], v[84:87]
	s_barrier
	s_add_i32 s23, 0, 0x14000
	s_add_i32 s24, s25, s37
	v_add_u32_e32 v145, s23, v143
	v_lshl_add_u64 v[194:195], s[50:51], 0, v[132:133]
	s_mov_b32 m0, s24
	ds_read_b128 v[202:205], v145
	ds_read_b128 v[206:209], v145 offset:1024
	ds_read_b128 v[210:213], v145 offset:2048
	ds_read_b128 v[214:217], v145 offset:3072
	global_load_lds_dwordx4 v[194:195], off
	v_lshl_add_u64 v[198:199], s[50:51], 0, v[136:137]
	s_add_i32 m0, s24, 0x2000
	s_nop 0
	global_load_lds_dwordx4 v[198:199], off
	s_barrier
	s_waitcnt lgkmcnt(0)
	s_waitcnt lgkmcnt(0)
	v_mfma_f32_16x16x32_bf16 v[112:115], v[202:205], v[162:165], v[112:115]
	v_mfma_f32_16x16x32_bf16 v[108:111], v[210:213], v[162:165], v[108:111]
	v_mfma_f32_16x16x32_bf16 v[96:99], v[202:205], v[170:173], v[96:99]
	v_mfma_f32_16x16x32_bf16 v[92:95], v[210:213], v[170:173], v[92:95]
	v_mfma_f32_16x16x32_bf16 v[80:83], v[202:205], v[178:181], v[80:83]
	v_mfma_f32_16x16x32_bf16 v[76:79], v[210:213], v[178:181], v[76:79]
	v_mfma_f32_16x16x32_bf16 v[72:75], v[202:205], v[186:189], v[72:75]
	v_mfma_f32_16x16x32_bf16 v[68:71], v[210:213], v[186:189], v[68:71]
	v_mfma_f32_16x16x32_bf16 v[112:115], v[206:209], v[166:169], v[112:115]
	v_mfma_f32_16x16x32_bf16 v[108:111], v[214:217], v[166:169], v[108:111]
	v_mfma_f32_16x16x32_bf16 v[96:99], v[206:209], v[174:177], v[96:99]
	v_mfma_f32_16x16x32_bf16 v[92:95], v[214:217], v[174:177], v[92:95]
	v_mfma_f32_16x16x32_bf16 v[80:83], v[206:209], v[182:185], v[80:83]
	v_mfma_f32_16x16x32_bf16 v[76:79], v[214:217], v[182:185], v[76:79]
	v_mfma_f32_16x16x32_bf16 v[72:75], v[206:209], v[190:193], v[72:75]
	v_mfma_f32_16x16x32_bf16 v[68:71], v[214:217], v[190:193], v[68:71]
	s_mov_b32 m0, s54
	v_lshl_add_u64 v[222:223], s[52:53], 0, v[0:1]
	s_barrier
	ds_read_b128 v[162:165], v144 offset:16384
	ds_read_b128 v[166:169], v144 offset:17408
	ds_read_b128 v[170:173], v144 offset:18432
	ds_read_b128 v[174:177], v144 offset:19456
	ds_read_b128 v[178:181], v144 offset:20480
	ds_read_b128 v[182:185], v144 offset:21504
	ds_read_b128 v[186:189], v144 offset:22528
	ds_read_b128 v[190:193], v144 offset:23552
	global_load_lds_dwordx4 v[222:223], off
	v_lshl_add_u64 v[236:237], s[52:53], 0, v[134:135]
	s_mov_b32 m0, s55
	s_nop 0
	global_load_lds_dwordx4 v[236:237], off
	s_barrier
	s_waitcnt lgkmcnt(0)
	s_waitcnt lgkmcnt(0)
	v_mfma_f32_16x16x32_bf16 v[64:67], v[146:149], v[162:165], v[64:67]
	v_mfma_f32_16x16x32_bf16 v[60:63], v[154:157], v[162:165], v[60:63]
	v_mfma_f32_16x16x32_bf16 v[56:59], v[146:149], v[170:173], v[56:59]
	v_mfma_f32_16x16x32_bf16 v[52:55], v[154:157], v[170:173], v[52:55]
	v_mfma_f32_16x16x32_bf16 v[40:43], v[146:149], v[178:181], v[40:43]
	v_mfma_f32_16x16x32_bf16 v[36:39], v[154:157], v[178:181], v[36:39]
	v_mfma_f32_16x16x32_bf16 v[24:27], v[146:149], v[186:189], v[24:27]
	v_mfma_f32_16x16x32_bf16 v[16:19], v[154:157], v[186:189], v[16:19]
	v_mfma_f32_16x16x32_bf16 v[64:67], v[150:153], v[166:169], v[64:67]
	v_mfma_f32_16x16x32_bf16 v[60:63], v[158:161], v[166:169], v[60:63]
	v_mfma_f32_16x16x32_bf16 v[56:59], v[150:153], v[174:177], v[56:59]
	v_mfma_f32_16x16x32_bf16 v[52:55], v[158:161], v[174:177], v[52:55]
	v_mfma_f32_16x16x32_bf16 v[40:43], v[150:153], v[182:185], v[40:43]
	v_mfma_f32_16x16x32_bf16 v[36:39], v[158:161], v[182:185], v[36:39]
	v_mfma_f32_16x16x32_bf16 v[24:27], v[150:153], v[190:193], v[24:27]
	v_mfma_f32_16x16x32_bf16 v[16:19], v[158:161], v[190:193], v[16:19]
	s_barrier
	s_add_u32 s24, s50, 0x40000
	s_addc_u32 s25, s51, 0
	s_add_i32 s23, s23, s37
	v_lshl_add_u64 v[146:147], s[24:25], 0, v[132:133]
	s_mov_b32 m0, s23
	s_nop 0
	global_load_lds_dwordx4 v[146:147], off
	v_lshl_add_u64 v[146:147], s[24:25], 0, v[136:137]
	s_add_i32 m0, s23, 0x2000
	s_nop 0
	global_load_lds_dwordx4 v[146:147], off
	s_waitcnt vmcnt(6)
	s_barrier
	v_mfma_f32_16x16x32_bf16 v[48:51], v[202:205], v[162:165], v[48:51]
	v_mfma_f32_16x16x32_bf16 v[44:47], v[210:213], v[162:165], v[44:47]
	v_mfma_f32_16x16x32_bf16 v[32:35], v[202:205], v[170:173], v[32:35]
	v_mfma_f32_16x16x32_bf16 v[28:31], v[210:213], v[170:173], v[28:31]
	v_mfma_f32_16x16x32_bf16 v[20:23], v[202:205], v[178:181], v[20:23]
	v_mfma_f32_16x16x32_bf16 v[12:15], v[210:213], v[178:181], v[12:15]
	v_mfma_f32_16x16x32_bf16 v[8:11], v[202:205], v[186:189], v[8:11]
	v_mfma_f32_16x16x32_bf16 v[4:7], v[210:213], v[186:189], v[4:7]
	v_mfma_f32_16x16x32_bf16 v[48:51], v[206:209], v[166:169], v[48:51]
	v_mfma_f32_16x16x32_bf16 v[44:47], v[214:217], v[166:169], v[44:47]
	v_mfma_f32_16x16x32_bf16 v[32:35], v[206:209], v[174:177], v[32:35]
	v_mfma_f32_16x16x32_bf16 v[28:31], v[214:217], v[174:177], v[28:31]
	v_mfma_f32_16x16x32_bf16 v[20:23], v[206:209], v[182:185], v[20:23]
	v_mfma_f32_16x16x32_bf16 v[12:15], v[214:217], v[182:185], v[12:15]
	v_mfma_f32_16x16x32_bf16 v[8:11], v[206:209], v[190:193], v[8:11]
	v_mfma_f32_16x16x32_bf16 v[4:7], v[214:217], v[190:193], v[4:7]
	s_add_i32 s23, 0, 0x18000
	v_add_u32_e32 v145, s23, v143
	s_barrier
	ds_read_b128 v[146:149], v145
	ds_read_b128 v[150:153], v145 offset:1024
	ds_read_b128 v[154:157], v145 offset:2048
	ds_read_b128 v[158:161], v145 offset:3072
	s_add_u32 s24, s52, 0x40000
	s_addc_u32 s25, s53, 0
	s_mov_b32 m0, s56
	v_lshl_add_u64 v[202:203], s[24:25], 0, v[0:1]
	ds_read_b128 v[162:165], v144 offset:32768
	ds_read_b128 v[166:169], v144 offset:33792
	ds_read_b128 v[170:173], v144 offset:34816
	ds_read_b128 v[174:177], v144 offset:35840
	ds_read_b128 v[178:181], v144 offset:36864
	ds_read_b128 v[182:185], v144 offset:37888
	ds_read_b128 v[186:189], v144 offset:38912
	ds_read_b128 v[190:193], v144 offset:39936
	global_load_lds_dwordx4 v[202:203], off
	v_lshl_add_u64 v[202:203], s[24:25], 0, v[134:135]
	s_mov_b32 m0, s57
	s_nop 0
	global_load_lds_dwordx4 v[202:203], off
	s_waitcnt lgkmcnt(8)
	s_barrier
	s_waitcnt lgkmcnt(0)
	s_waitcnt lgkmcnt(0)
	v_mfma_f32_16x16x32_bf16 v[128:131], v[146:149], v[162:165], v[128:131]
	v_mfma_f32_16x16x32_bf16 v[124:127], v[154:157], v[162:165], v[124:127]
	v_mfma_f32_16x16x32_bf16 v[120:123], v[146:149], v[170:173], v[120:123]
	v_mfma_f32_16x16x32_bf16 v[116:119], v[154:157], v[170:173], v[116:119]
	v_mfma_f32_16x16x32_bf16 v[104:107], v[146:149], v[178:181], v[104:107]
	v_mfma_f32_16x16x32_bf16 v[100:103], v[154:157], v[178:181], v[100:103]
	v_mfma_f32_16x16x32_bf16 v[88:91], v[146:149], v[186:189], v[88:91]
	v_mfma_f32_16x16x32_bf16 v[84:87], v[154:157], v[186:189], v[84:87]
	v_mfma_f32_16x16x32_bf16 v[128:131], v[150:153], v[166:169], v[128:131]
	v_mfma_f32_16x16x32_bf16 v[124:127], v[158:161], v[166:169], v[124:127]
	v_mfma_f32_16x16x32_bf16 v[120:123], v[150:153], v[174:177], v[120:123]
	v_mfma_f32_16x16x32_bf16 v[116:119], v[158:161], v[174:177], v[116:119]
	v_mfma_f32_16x16x32_bf16 v[104:107], v[150:153], v[182:185], v[104:107]
	v_mfma_f32_16x16x32_bf16 v[100:103], v[158:161], v[182:185], v[100:103]
	v_mfma_f32_16x16x32_bf16 v[88:91], v[150:153], v[190:193], v[88:91]
	v_mfma_f32_16x16x32_bf16 v[84:87], v[158:161], v[190:193], v[84:87]
	s_barrier
	s_add_i32 s26, 0, 0x1c000
	s_add_i32 s23, s23, s37
	v_add_u32_e32 v145, s26, v143
	v_lshl_add_u64 v[194:195], v[194:195], 0, s[76:77]
	s_mov_b32 m0, s23
	ds_read_b128 v[202:205], v145
	ds_read_b128 v[206:209], v145 offset:1024
	ds_read_b128 v[210:213], v145 offset:2048
	ds_read_b128 v[214:217], v145 offset:3072
	global_load_lds_dwordx4 v[194:195], off
	v_lshl_add_u64 v[194:195], v[198:199], 0, s[76:77]
	s_add_i32 m0, s23, 0x2000
	s_nop 0
	global_load_lds_dwordx4 v[194:195], off
	s_barrier
	s_waitcnt lgkmcnt(0)
	s_waitcnt lgkmcnt(0)
	v_mfma_f32_16x16x32_bf16 v[112:115], v[202:205], v[162:165], v[112:115]
	v_mfma_f32_16x16x32_bf16 v[108:111], v[210:213], v[162:165], v[108:111]
	v_mfma_f32_16x16x32_bf16 v[96:99], v[202:205], v[170:173], v[96:99]
	v_mfma_f32_16x16x32_bf16 v[92:95], v[210:213], v[170:173], v[92:95]
	v_mfma_f32_16x16x32_bf16 v[80:83], v[202:205], v[178:181], v[80:83]
	v_mfma_f32_16x16x32_bf16 v[76:79], v[210:213], v[178:181], v[76:79]
	v_mfma_f32_16x16x32_bf16 v[72:75], v[202:205], v[186:189], v[72:75]
	v_mfma_f32_16x16x32_bf16 v[68:71], v[210:213], v[186:189], v[68:71]
	v_mfma_f32_16x16x32_bf16 v[112:115], v[206:209], v[166:169], v[112:115]
	v_mfma_f32_16x16x32_bf16 v[108:111], v[214:217], v[166:169], v[108:111]
	v_mfma_f32_16x16x32_bf16 v[96:99], v[206:209], v[174:177], v[96:99]
	v_mfma_f32_16x16x32_bf16 v[92:95], v[214:217], v[174:177], v[92:95]
	v_mfma_f32_16x16x32_bf16 v[80:83], v[206:209], v[182:185], v[80:83]
	v_mfma_f32_16x16x32_bf16 v[76:79], v[214:217], v[182:185], v[76:79]
	v_mfma_f32_16x16x32_bf16 v[72:75], v[206:209], v[190:193], v[72:75]
	v_mfma_f32_16x16x32_bf16 v[68:71], v[214:217], v[190:193], v[68:71]
	s_mov_b32 m0, s59
	v_lshl_add_u64 v[194:195], v[222:223], 0, s[76:77]
	s_barrier
	ds_read_b128 v[162:165], v144 offset:49152
	ds_read_b128 v[166:169], v144 offset:50176
	ds_read_b128 v[170:173], v144 offset:51200
	ds_read_b128 v[174:177], v144 offset:52224
	ds_read_b128 v[178:181], v144 offset:53248
	ds_read_b128 v[182:185], v144 offset:54272
	ds_read_b128 v[186:189], v144 offset:55296
	ds_read_b128 v[190:193], v144 offset:56320
	global_load_lds_dwordx4 v[194:195], off
	v_lshl_add_u64 v[194:195], v[236:237], 0, s[76:77]
	s_mov_b32 m0, s60
	s_nop 0
	global_load_lds_dwordx4 v[194:195], off
	s_barrier
	s_waitcnt lgkmcnt(0)
	s_waitcnt lgkmcnt(0)
	v_mfma_f32_16x16x32_bf16 v[64:67], v[146:149], v[162:165], v[64:67]
	v_mfma_f32_16x16x32_bf16 v[60:63], v[154:157], v[162:165], v[60:63]
	v_mfma_f32_16x16x32_bf16 v[56:59], v[146:149], v[170:173], v[56:59]
	v_mfma_f32_16x16x32_bf16 v[52:55], v[154:157], v[170:173], v[52:55]
	v_mfma_f32_16x16x32_bf16 v[40:43], v[146:149], v[178:181], v[40:43]
	v_mfma_f32_16x16x32_bf16 v[36:39], v[154:157], v[178:181], v[36:39]
	v_mfma_f32_16x16x32_bf16 v[24:27], v[146:149], v[186:189], v[24:27]
	v_mfma_f32_16x16x32_bf16 v[16:19], v[154:157], v[186:189], v[16:19]
	v_mfma_f32_16x16x32_bf16 v[64:67], v[150:153], v[166:169], v[64:67]
	v_mfma_f32_16x16x32_bf16 v[60:63], v[158:161], v[166:169], v[60:63]
	v_mfma_f32_16x16x32_bf16 v[56:59], v[150:153], v[174:177], v[56:59]
	v_mfma_f32_16x16x32_bf16 v[52:55], v[158:161], v[174:177], v[52:55]
	v_mfma_f32_16x16x32_bf16 v[40:43], v[150:153], v[182:185], v[40:43]
	v_mfma_f32_16x16x32_bf16 v[36:39], v[158:161], v[182:185], v[36:39]
	v_mfma_f32_16x16x32_bf16 v[24:27], v[150:153], v[190:193], v[24:27]
	v_mfma_f32_16x16x32_bf16 v[16:19], v[158:161], v[190:193], v[16:19]
	s_barrier
	s_add_u32 s24, s50, 0x40080
	s_addc_u32 s25, s51, 0
	s_add_i32 s23, s26, s37
	v_lshl_add_u64 v[146:147], s[24:25], 0, v[132:133]
	s_mov_b32 m0, s23
	s_nop 0
	global_load_lds_dwordx4 v[146:147], off
	v_lshl_add_u64 v[146:147], s[24:25], 0, v[136:137]
	s_add_i32 m0, s23, 0x2000
	s_nop 0
	global_load_lds_dwordx4 v[146:147], off
	s_waitcnt vmcnt(6)
	s_barrier
	v_mfma_f32_16x16x32_bf16 v[48:51], v[202:205], v[162:165], v[48:51]
	v_mfma_f32_16x16x32_bf16 v[44:47], v[210:213], v[162:165], v[44:47]
	v_mfma_f32_16x16x32_bf16 v[32:35], v[202:205], v[170:173], v[32:35]
	v_mfma_f32_16x16x32_bf16 v[28:31], v[210:213], v[170:173], v[28:31]
	v_mfma_f32_16x16x32_bf16 v[20:23], v[202:205], v[178:181], v[20:23]
	v_mfma_f32_16x16x32_bf16 v[12:15], v[210:213], v[178:181], v[12:15]
	v_mfma_f32_16x16x32_bf16 v[8:11], v[202:205], v[186:189], v[8:11]
	v_mfma_f32_16x16x32_bf16 v[4:7], v[210:213], v[186:189], v[4:7]
	v_mfma_f32_16x16x32_bf16 v[48:51], v[206:209], v[166:169], v[48:51]
	v_mfma_f32_16x16x32_bf16 v[44:47], v[214:217], v[166:169], v[44:47]
	v_mfma_f32_16x16x32_bf16 v[32:35], v[206:209], v[174:177], v[32:35]
	v_mfma_f32_16x16x32_bf16 v[28:31], v[214:217], v[174:177], v[28:31]
	v_mfma_f32_16x16x32_bf16 v[20:23], v[206:209], v[182:185], v[20:23]
	v_mfma_f32_16x16x32_bf16 v[12:15], v[214:217], v[182:185], v[12:15]
	v_mfma_f32_16x16x32_bf16 v[8:11], v[206:209], v[190:193], v[8:11]
	v_mfma_f32_16x16x32_bf16 v[4:7], v[214:217], v[190:193], v[4:7]
	s_add_i32 s22, s22, 2
	s_add_u32 s48, s48, 0x100
	s_addc_u32 s49, s49, 0
	s_add_u32 s20, s20, 0x100
	s_addc_u32 s21, s21, 0
	s_cmp_gt_u32 s22, 13
	s_barrier
	s_cbranch_scc0 .LBB0_136
	v_lshl_add_u32 v146, s0, 8, v142
	v_cvt_pk_bf16_f32 v72, v72, v73
	v_cvt_pk_bf16_f32 v73, v74, v75
	v_cvt_pk_bf16_f32 v74, v68, v69
	v_add_u32_e32 v68, 0x80, v146
	s_lshl_b32 s0, s1, 8
	v_ashrrev_i32_e32 v147, 31, v146
	v_readlane_b32 s20, v252, 12
	v_cvt_pk_bf16_f32 v112, v112, v113
	v_cvt_pk_bf16_f32 v113, v114, v115
	v_cvt_pk_bf16_f32 v114, v108, v109
	v_or_b32_e32 v108, 16, v146
	v_ashrrev_i32_e32 v69, 31, v68
	v_cvt_pk_bf16_f32 v48, v48, v49
	v_cvt_pk_bf16_f32 v49, v50, v51
	v_cvt_pk_bf16_f32 v50, v44, v45
	v_add_u32_e32 v44, 0x90, v146
	s_ashr_i32 s1, s0, 31
	v_lshlrev_b64 v[148:149], 11, v[146:147]
	v_readlane_b32 s21, v252, 13
	v_ashrrev_i32_e32 v109, 31, v108
	v_cvt_pk_bf16_f32 v96, v96, v97
	v_cvt_pk_bf16_f32 v97, v98, v99
	v_cvt_pk_bf16_f32 v98, v92, v93
	v_or_b32_e32 v92, 32, v146
	v_lshlrev_b64 v[68:69], 11, v[68:69]
	v_ashrrev_i32_e32 v45, 31, v44
	v_cvt_pk_bf16_f32 v32, v32, v33
	v_cvt_pk_bf16_f32 v33, v34, v35
	v_cvt_pk_bf16_f32 v34, v28, v29
	v_add_u32_e32 v28, 0xa0, v146
	v_lshl_add_u64 v[148:149], s[20:21], 0, v[148:149]
	s_lshl_b64 s[0:1], s[0:1], 1
	v_lshlrev_b64 v[108:109], 11, v[108:109]
	v_ashrrev_i32_e32 v93, 31, v92
	v_cvt_pk_bf16_f32 v80, v80, v81
	v_cvt_pk_bf16_f32 v81, v82, v83
	v_cvt_pk_bf16_f32 v82, v76, v77
	v_or_b32_e32 v76, 48, v146
	v_lshl_add_u64 v[68:69], s[20:21], 0, v[68:69]
	v_lshlrev_b64 v[44:45], 11, v[44:45]
	v_ashrrev_i32_e32 v29, 31, v28
	v_cvt_pk_bf16_f32 v20, v20, v21
	v_cvt_pk_bf16_f32 v21, v22, v23
	v_cvt_pk_bf16_f32 v22, v12, v13
	v_add_u32_e32 v12, 0xb0, v146
	v_lshl_add_u64 v[148:149], v[148:149], 0, s[0:1]
	v_lshl_add_u64 v[108:109], s[20:21], 0, v[108:109]
	v_lshlrev_b64 v[92:93], 11, v[92:93]
	v_ashrrev_i32_e32 v77, 31, v76
	v_lshl_add_u64 v[68:69], v[68:69], 0, s[0:1]
	v_lshl_add_u64 v[44:45], s[20:21], 0, v[44:45]
	v_lshlrev_b64 v[28:29], 11, v[28:29]
	v_ashrrev_i32_e32 v13, 31, v12
	v_lshl_add_u64 v[148:149], v[148:149], 0, s[72:73]
	v_lshl_add_u64 v[108:109], v[108:109], 0, s[0:1]
	v_lshl_add_u64 v[92:93], s[20:21], 0, v[92:93]
	v_lshlrev_b64 v[76:77], 11, v[76:77]
	v_lshl_add_u64 v[68:69], v[68:69], 0, s[72:73]
	v_lshl_add_u64 v[44:45], v[44:45], 0, s[0:1]
	v_lshl_add_u64 v[28:29], s[20:21], 0, v[28:29]
	v_lshlrev_b64 v[12:13], 11, v[12:13]
	v_lshl_add_u64 v[148:149], v[148:149], 0, v[2:3]
	v_cvt_pk_bf16_f32 v115, v110, v111
	v_lshl_add_u64 v[108:109], v[108:109], 0, s[72:73]
	v_lshl_add_u64 v[92:93], v[92:93], 0, s[0:1]
	v_lshl_add_u64 v[76:77], s[20:21], 0, v[76:77]
	v_lshl_add_u64 v[68:69], v[68:69], 0, v[2:3]
	v_cvt_pk_bf16_f32 v51, v46, v47
	v_lshl_add_u64 v[44:45], v[44:45], 0, s[72:73]
	v_lshl_add_u64 v[28:29], v[28:29], 0, s[0:1]
	v_lshl_add_u64 v[12:13], s[20:21], 0, v[12:13]
	global_store_dwordx4 v[148:149], v[112:115], off offset:256
	v_cvt_pk_bf16_f32 v99, v94, v95
	v_lshl_add_u64 v[92:93], v[92:93], 0, s[72:73]
	v_lshl_add_u64 v[112:113], v[108:109], 0, v[2:3]
	v_lshl_add_u64 v[76:77], v[76:77], 0, s[0:1]
	global_store_dwordx4 v[68:69], v[48:51], off offset:256
	v_cvt_pk_bf16_f32 v35, v30, v31
	v_lshl_add_u64 v[28:29], v[28:29], 0, s[72:73]
	v_lshl_add_u64 v[48:49], v[44:45], 0, v[2:3]
	v_lshl_add_u64 v[12:13], v[12:13], 0, s[0:1]
	global_store_dwordx4 v[112:113], v[96:99], off offset:256
	v_cvt_pk_bf16_f32 v83, v78, v79
	v_lshl_add_u64 v[76:77], v[76:77], 0, s[72:73]
	v_lshl_add_u64 v[96:97], v[92:93], 0, v[2:3]
	global_store_dwordx4 v[48:49], v[32:35], off offset:256
	v_cvt_pk_bf16_f32 v23, v14, v15
	v_lshl_add_u64 v[12:13], v[12:13], 0, s[72:73]
	v_lshl_add_u64 v[32:33], v[28:29], 0, v[2:3]
	v_cvt_pk_bf16_f32 v128, v128, v129
	v_cvt_pk_bf16_f32 v129, v130, v131
	v_cvt_pk_bf16_f32 v130, v124, v125
	v_cvt_pk_bf16_f32 v131, v126, v127
	v_cvt_pk_bf16_f32 v108, v120, v121
	v_cvt_pk_bf16_f32 v109, v122, v123
	v_cvt_pk_bf16_f32 v110, v116, v117
	v_cvt_pk_bf16_f32 v111, v118, v119
	v_cvt_pk_bf16_f32 v92, v104, v105
	v_cvt_pk_bf16_f32 v93, v106, v107
	v_cvt_pk_bf16_f32 v94, v100, v101
	v_cvt_pk_bf16_f32 v95, v102, v103
	global_store_dwordx4 v[96:97], v[80:83], off offset:256
	v_cvt_pk_bf16_f32 v78, v84, v85
	v_cvt_pk_bf16_f32 v79, v86, v87
	v_lshl_add_u64 v[80:81], v[76:77], 0, v[2:3]
	v_cvt_pk_bf16_f32 v76, v88, v89
	v_cvt_pk_bf16_f32 v77, v90, v91
	v_cvt_pk_bf16_f32 v75, v70, v71
	v_cvt_pk_bf16_f32 v64, v64, v65
	v_cvt_pk_bf16_f32 v65, v66, v67
	v_cvt_pk_bf16_f32 v66, v60, v61
	v_cvt_pk_bf16_f32 v67, v62, v63
	v_cvt_pk_bf16_f32 v44, v56, v57
	v_cvt_pk_bf16_f32 v45, v58, v59
	v_cvt_pk_bf16_f32 v46, v52, v53
	v_cvt_pk_bf16_f32 v47, v54, v55
	v_cvt_pk_bf16_f32 v28, v40, v41
	v_cvt_pk_bf16_f32 v29, v42, v43
	v_cvt_pk_bf16_f32 v30, v36, v37
	v_cvt_pk_bf16_f32 v31, v38, v39
	global_store_dwordx4 v[32:33], v[20:23], off offset:256
	v_cvt_pk_bf16_f32 v14, v16, v17
	v_cvt_pk_bf16_f32 v15, v18, v19
	v_lshl_add_u64 v[20:21], v[12:13], 0, v[2:3]
	v_cvt_pk_bf16_f32 v12, v24, v25
	v_cvt_pk_bf16_f32 v13, v26, v27
	v_cvt_pk_bf16_f32 v8, v8, v9
	v_cvt_pk_bf16_f32 v9, v10, v11
	v_cvt_pk_bf16_f32 v10, v4, v5
	v_cvt_pk_bf16_f32 v11, v6, v7
	s_and_b64 vcc, exec, s[38:39]
	s_mov_b32 s1, s40
	s_mov_b32 s0, s42
	s_mov_b64 s[50:51], s[46:47]
	s_mov_b64 s[48:49], s[44:45]
	global_store_dwordx4 v[148:149], v[128:131], off
	global_store_dwordx4 v[112:113], v[108:111], off
	global_store_dwordx4 v[96:97], v[92:95], off
	global_store_dwordx4 v[80:81], v[76:79], off
	global_store_dwordx4 v[80:81], v[72:75], off offset:256
	global_store_dwordx4 v[68:69], v[64:67], off
	global_store_dwordx4 v[48:49], v[44:47], off
	global_store_dwordx4 v[32:33], v[28:31], off
	global_store_dwordx4 v[20:21], v[12:15], off
	global_store_dwordx4 v[20:21], v[8:11], off offset:256
	s_cbranch_vccz .LBB0_129
	s_waitcnt vmcnt(0)
	s_cmpk_gt_u32 s31, 0xff
	s_cbranch_scc1 .LBB0_140
	s_barrier

.LBB0_175:
	s_add_i32 s26, s27, 2
	s_add_u32 s44, s40, 0x100
	s_addc_u32 s45, s41, 0
	s_add_i32 s30, 0, 0x10000
	v_add_u32_e32 v0, s30, v157
	ds_read_b128 v[132:135], v0
	ds_read_b128 v[164:167], v0 offset:1024
	ds_read_b128 v[168:171], v0 offset:2048
	ds_read_b128 v[174:177], v0 offset:3072
	s_cmp_eq_u32 s23, s27
	s_cselect_b32 s49, s1, s45
	s_cselect_b32 s48, s0, s44
	s_cselect_b32 s47, s43, s25
	s_cselect_b32 s46, s42, s24
	v_lshl_add_u64 v[0:1], s[40:41], 0, v[160:161]
	s_add_i32 m0, s53, 0xc000
	ds_read_b128 v[178:181], v172
	ds_read_b128 v[182:185], v172 offset:1024
	ds_read_b128 v[186:189], v172 offset:2048
	ds_read_b128 v[190:193], v172 offset:3072
	ds_read_b128 v[202:205], v172 offset:4096
	ds_read_b128 v[206:209], v172 offset:5120
	ds_read_b128 v[210:213], v172 offset:6144
	ds_read_b128 v[214:217], v172 offset:7168
	global_load_lds_dwordx4 v[0:1], off
	v_lshl_add_u64 v[0:1], s[40:41], 0, v[162:163]
	s_add_i32 m0, s53, 0xe000
	s_nop 0
	global_load_lds_dwordx4 v[0:1], off
	s_waitcnt lgkmcnt(8)
	s_barrier
	s_waitcnt lgkmcnt(0)
	s_waitcnt lgkmcnt(0)
	v_mfma_f32_16x16x32_bf16 v[4:7], v[132:135], v[178:181], v[4:7]
	v_mfma_f32_16x16x32_bf16 v[8:11], v[168:171], v[178:181], v[8:11]
	v_mfma_f32_16x16x32_bf16 v[128:131], v[132:135], v[186:189], v[128:131]
	v_mfma_f32_16x16x32_bf16 v[124:127], v[168:171], v[186:189], v[124:127]
	v_mfma_f32_16x16x32_bf16 v[120:123], v[132:135], v[202:205], v[120:123]
	v_mfma_f32_16x16x32_bf16 v[116:119], v[168:171], v[202:205], v[116:119]
	v_mfma_f32_16x16x32_bf16 v[112:115], v[132:135], v[210:213], v[112:115]
	v_mfma_f32_16x16x32_bf16 v[108:111], v[168:171], v[210:213], v[108:111]
	v_mfma_f32_16x16x32_bf16 v[4:7], v[164:167], v[182:185], v[4:7]
	v_mfma_f32_16x16x32_bf16 v[8:11], v[174:177], v[182:185], v[8:11]
	v_mfma_f32_16x16x32_bf16 v[128:131], v[164:167], v[190:193], v[128:131]
	v_mfma_f32_16x16x32_bf16 v[124:127], v[174:177], v[190:193], v[124:127]
	v_mfma_f32_16x16x32_bf16 v[120:123], v[164:167], v[206:209], v[120:123]
	v_mfma_f32_16x16x32_bf16 v[116:119], v[174:177], v[206:209], v[116:119]
	v_mfma_f32_16x16x32_bf16 v[112:115], v[164:167], v[214:217], v[112:115]
	v_mfma_f32_16x16x32_bf16 v[108:111], v[174:177], v[214:217], v[108:111]
	s_barrier
	s_add_i32 s27, 0, 0x14000
	v_add_u32_e32 v0, s27, v157
	s_add_i32 s30, s30, s52
	ds_read_b128 v[236:239], v0
	ds_read_b128 v[240:243], v0 offset:1024
	ds_read_b128 v[244:247], v0 offset:2048
	ds_read_b128 v[248:251], v0 offset:3072
	v_lshl_add_u64 v[0:1], s[46:47], 0, v[138:139]
	s_mov_b32 m0, s30
	v_lshl_add_u64 v[194:195], s[46:47], 0, v[142:143]
	global_load_lds_dwordx4 v[0:1], off
	s_add_i32 m0, s30, 0x2000
	s_nop 0
	global_load_lds_dwordx4 v[194:195], off
	s_barrier
	s_waitcnt lgkmcnt(0)
	s_waitcnt lgkmcnt(0)
	v_mfma_f32_16x16x32_bf16 v[12:15], v[236:239], v[178:181], v[12:15]
	v_mfma_f32_16x16x32_bf16 v[16:19], v[244:247], v[178:181], v[16:19]
	v_mfma_f32_16x16x32_bf16 v[104:107], v[236:239], v[186:189], v[104:107]
	v_mfma_f32_16x16x32_bf16 v[100:103], v[244:247], v[186:189], v[100:103]
	v_mfma_f32_16x16x32_bf16 v[96:99], v[236:239], v[202:205], v[96:99]
	v_mfma_f32_16x16x32_bf16 v[92:95], v[244:247], v[202:205], v[92:95]
	v_mfma_f32_16x16x32_bf16 v[88:91], v[236:239], v[210:213], v[88:91]
	v_mfma_f32_16x16x32_bf16 v[84:87], v[244:247], v[210:213], v[84:87]
	v_mfma_f32_16x16x32_bf16 v[12:15], v[240:243], v[182:185], v[12:15]
	v_mfma_f32_16x16x32_bf16 v[16:19], v[248:251], v[182:185], v[16:19]
	v_mfma_f32_16x16x32_bf16 v[104:107], v[240:243], v[190:193], v[104:107]
	v_mfma_f32_16x16x32_bf16 v[100:103], v[248:251], v[190:193], v[100:103]
	v_mfma_f32_16x16x32_bf16 v[96:99], v[240:243], v[206:209], v[96:99]
	v_mfma_f32_16x16x32_bf16 v[92:95], v[248:251], v[206:209], v[92:95]
	v_mfma_f32_16x16x32_bf16 v[88:91], v[240:243], v[214:217], v[88:91]
	v_mfma_f32_16x16x32_bf16 v[84:87], v[248:251], v[214:217], v[84:87]
	s_mov_b32 m0, s53
	v_lshl_add_u64 v[222:223], s[48:49], 0, v[136:137]
	s_barrier
	ds_read_b128 v[178:181], v172 offset:16384
	ds_read_b128 v[182:185], v172 offset:17408
	ds_read_b128 v[186:189], v172 offset:18432
	ds_read_b128 v[190:193], v172 offset:19456
	ds_read_b128 v[202:205], v172 offset:20480
	ds_read_b128 v[206:209], v172 offset:21504
	ds_read_b128 v[210:213], v172 offset:22528
	ds_read_b128 v[214:217], v172 offset:23552
	global_load_lds_dwordx4 v[222:223], off
	v_lshl_add_u64 v[198:199], s[48:49], 0, v[140:141]
	s_mov_b32 m0, s54
	s_nop 0
	global_load_lds_dwordx4 v[198:199], off
	s_barrier
	s_waitcnt lgkmcnt(0)
	s_waitcnt lgkmcnt(0)
	v_mfma_f32_16x16x32_bf16 v[80:83], v[132:135], v[178:181], v[80:83]
	v_mfma_f32_16x16x32_bf16 v[76:79], v[168:171], v[178:181], v[76:79]
	v_mfma_f32_16x16x32_bf16 v[72:75], v[132:135], v[186:189], v[72:75]
	v_mfma_f32_16x16x32_bf16 v[68:71], v[168:171], v[186:189], v[68:71]
	v_mfma_f32_16x16x32_bf16 v[64:67], v[132:135], v[202:205], v[64:67]
	v_mfma_f32_16x16x32_bf16 v[60:63], v[168:171], v[202:205], v[60:63]
	v_mfma_f32_16x16x32_bf16 v[56:59], v[132:135], v[210:213], v[56:59]
	v_mfma_f32_16x16x32_bf16 v[52:55], v[168:171], v[210:213], v[52:55]
	v_mfma_f32_16x16x32_bf16 v[80:83], v[164:167], v[182:185], v[80:83]
	v_mfma_f32_16x16x32_bf16 v[76:79], v[174:177], v[182:185], v[76:79]
	v_mfma_f32_16x16x32_bf16 v[72:75], v[164:167], v[190:193], v[72:75]
	v_mfma_f32_16x16x32_bf16 v[68:71], v[174:177], v[190:193], v[68:71]
	v_mfma_f32_16x16x32_bf16 v[64:67], v[164:167], v[206:209], v[64:67]
	v_mfma_f32_16x16x32_bf16 v[60:63], v[174:177], v[206:209], v[60:63]
	v_mfma_f32_16x16x32_bf16 v[56:59], v[164:167], v[214:217], v[56:59]
	v_mfma_f32_16x16x32_bf16 v[52:55], v[174:177], v[214:217], v[52:55]
	s_barrier
	s_add_u32 s30, s46, 0xc0000
	s_addc_u32 s31, s47, 0
	s_add_i32 s27, s27, s52
	v_lshl_add_u64 v[132:133], s[30:31], 0, v[138:139]
	s_mov_b32 m0, s27
	s_nop 0
	global_load_lds_dwordx4 v[132:133], off
	v_lshl_add_u64 v[132:133], s[30:31], 0, v[142:143]
	s_add_i32 m0, s27, 0x2000
	s_nop 0
	global_load_lds_dwordx4 v[132:133], off
	s_waitcnt vmcnt(6)
	s_barrier
	v_mfma_f32_16x16x32_bf16 v[48:51], v[236:239], v[178:181], v[48:51]
	v_mfma_f32_16x16x32_bf16 v[44:47], v[244:247], v[178:181], v[44:47]
	v_mfma_f32_16x16x32_bf16 v[40:43], v[236:239], v[186:189], v[40:43]
	v_mfma_f32_16x16x32_bf16 v[36:39], v[244:247], v[186:189], v[36:39]
	v_mfma_f32_16x16x32_bf16 v[32:35], v[236:239], v[202:205], v[32:35]
	v_mfma_f32_16x16x32_bf16 v[28:31], v[244:247], v[202:205], v[28:31]
	v_mfma_f32_16x16x32_bf16 v[24:27], v[236:239], v[210:213], v[24:27]
	v_mfma_f32_16x16x32_bf16 v[20:23], v[244:247], v[210:213], v[20:23]
	v_mfma_f32_16x16x32_bf16 v[48:51], v[240:243], v[182:185], v[48:51]
	v_mfma_f32_16x16x32_bf16 v[44:47], v[248:251], v[182:185], v[44:47]
	v_mfma_f32_16x16x32_bf16 v[40:43], v[240:243], v[190:193], v[40:43]
	v_mfma_f32_16x16x32_bf16 v[36:39], v[248:251], v[190:193], v[36:39]
	v_mfma_f32_16x16x32_bf16 v[32:35], v[240:243], v[206:209], v[32:35]
	v_mfma_f32_16x16x32_bf16 v[28:31], v[248:251], v[206:209], v[28:31]
	v_mfma_f32_16x16x32_bf16 v[24:27], v[240:243], v[214:217], v[24:27]
	v_mfma_f32_16x16x32_bf16 v[20:23], v[248:251], v[214:217], v[20:23]
	s_add_i32 s27, 0, 0x18000
	v_add_u32_e32 v2, s27, v157
	s_barrier
	ds_read_b128 v[132:135], v2
	ds_read_b128 v[164:167], v2 offset:1024
	ds_read_b128 v[168:171], v2 offset:2048
	ds_read_b128 v[174:177], v2 offset:3072
	s_add_u32 s30, s48, 0x1a0000
	s_addc_u32 s31, s49, 0
	s_mov_b32 m0, s55
	v_lshl_add_u64 v[236:237], s[30:31], 0, v[136:137]
	ds_read_b128 v[178:181], v172 offset:32768
	ds_read_b128 v[182:185], v172 offset:33792
	ds_read_b128 v[186:189], v172 offset:34816
	ds_read_b128 v[190:193], v172 offset:35840
	ds_read_b128 v[202:205], v172 offset:36864
	ds_read_b128 v[206:209], v172 offset:37888
	ds_read_b128 v[210:213], v172 offset:38912
	ds_read_b128 v[214:217], v172 offset:39936
	global_load_lds_dwordx4 v[236:237], off
	v_lshl_add_u64 v[236:237], s[30:31], 0, v[140:141]
	s_mov_b32 m0, s56
	s_nop 0
	global_load_lds_dwordx4 v[236:237], off
	s_waitcnt lgkmcnt(8)
	s_barrier
	s_waitcnt lgkmcnt(0)
	s_waitcnt lgkmcnt(0)
	v_mfma_f32_16x16x32_bf16 v[4:7], v[132:135], v[178:181], v[4:7]
	v_mfma_f32_16x16x32_bf16 v[8:11], v[168:171], v[178:181], v[8:11]
	v_mfma_f32_16x16x32_bf16 v[128:131], v[132:135], v[186:189], v[128:131]
	v_mfma_f32_16x16x32_bf16 v[124:127], v[168:171], v[186:189], v[124:127]
	v_mfma_f32_16x16x32_bf16 v[120:123], v[132:135], v[202:205], v[120:123]
	v_mfma_f32_16x16x32_bf16 v[116:119], v[168:171], v[202:205], v[116:119]
	v_mfma_f32_16x16x32_bf16 v[112:115], v[132:135], v[210:213], v[112:115]
	v_mfma_f32_16x16x32_bf16 v[108:111], v[168:171], v[210:213], v[108:111]
	v_mfma_f32_16x16x32_bf16 v[4:7], v[164:167], v[182:185], v[4:7]
	v_mfma_f32_16x16x32_bf16 v[8:11], v[174:177], v[182:185], v[8:11]
	v_mfma_f32_16x16x32_bf16 v[128:131], v[164:167], v[190:193], v[128:131]
	v_mfma_f32_16x16x32_bf16 v[124:127], v[174:177], v[190:193], v[124:127]
	v_mfma_f32_16x16x32_bf16 v[120:123], v[164:167], v[206:209], v[120:123]
	v_mfma_f32_16x16x32_bf16 v[116:119], v[174:177], v[206:209], v[116:119]
	v_mfma_f32_16x16x32_bf16 v[112:115], v[164:167], v[214:217], v[112:115]
	v_mfma_f32_16x16x32_bf16 v[108:111], v[174:177], v[214:217], v[108:111]
	s_barrier
	s_add_i32 s36, 0, 0x1c000
	s_add_i32 s27, s27, s52
	v_add_u32_e32 v2, s36, v157
	v_lshl_add_u64 v[0:1], v[0:1], 0, s[76:77]
	s_mov_b32 m0, s27
	ds_read_b128 v[236:239], v2
	ds_read_b128 v[240:243], v2 offset:1024
	ds_read_b128 v[244:247], v2 offset:2048
	ds_read_b128 v[248:251], v2 offset:3072
	global_load_lds_dwordx4 v[0:1], off
	v_lshl_add_u64 v[0:1], v[194:195], 0, s[76:77]
	s_add_i32 m0, s27, 0x2000
	s_nop 0
	global_load_lds_dwordx4 v[0:1], off
	s_barrier
	s_waitcnt lgkmcnt(0)
	s_waitcnt lgkmcnt(0)
	v_mfma_f32_16x16x32_bf16 v[12:15], v[236:239], v[178:181], v[12:15]
	v_mfma_f32_16x16x32_bf16 v[16:19], v[244:247], v[178:181], v[16:19]
	v_mfma_f32_16x16x32_bf16 v[104:107], v[236:239], v[186:189], v[104:107]
	v_mfma_f32_16x16x32_bf16 v[100:103], v[244:247], v[186:189], v[100:103]
	v_mfma_f32_16x16x32_bf16 v[96:99], v[236:239], v[202:205], v[96:99]
	v_mfma_f32_16x16x32_bf16 v[92:95], v[244:247], v[202:205], v[92:95]
	v_mfma_f32_16x16x32_bf16 v[88:91], v[236:239], v[210:213], v[88:91]
	v_mfma_f32_16x16x32_bf16 v[84:87], v[244:247], v[210:213], v[84:87]
	v_mfma_f32_16x16x32_bf16 v[12:15], v[240:243], v[182:185], v[12:15]
	v_mfma_f32_16x16x32_bf16 v[16:19], v[248:251], v[182:185], v[16:19]
	v_mfma_f32_16x16x32_bf16 v[104:107], v[240:243], v[190:193], v[104:107]
	v_mfma_f32_16x16x32_bf16 v[100:103], v[248:251], v[190:193], v[100:103]
	v_mfma_f32_16x16x32_bf16 v[96:99], v[240:243], v[206:209], v[96:99]
	v_mfma_f32_16x16x32_bf16 v[92:95], v[248:251], v[206:209], v[92:95]
	v_mfma_f32_16x16x32_bf16 v[88:91], v[240:243], v[214:217], v[88:91]
	v_mfma_f32_16x16x32_bf16 v[84:87], v[248:251], v[214:217], v[84:87]
	s_mov_b32 m0, s59
	v_lshl_add_u64 v[0:1], v[222:223], 0, s[76:77]
	s_barrier
	ds_read_b128 v[178:181], v172 offset:49152
	ds_read_b128 v[182:185], v172 offset:50176
	ds_read_b128 v[186:189], v172 offset:51200
	ds_read_b128 v[190:193], v172 offset:52224
	ds_read_b128 v[202:205], v172 offset:53248
	ds_read_b128 v[206:209], v172 offset:54272
	ds_read_b128 v[210:213], v172 offset:55296
	ds_read_b128 v[214:217], v172 offset:56320
	global_load_lds_dwordx4 v[0:1], off
	v_lshl_add_u64 v[0:1], v[198:199], 0, s[76:77]
	s_mov_b32 m0, s60
	s_nop 0
	global_load_lds_dwordx4 v[0:1], off
	s_barrier
	s_waitcnt lgkmcnt(0)
	s_waitcnt lgkmcnt(0)
	v_mfma_f32_16x16x32_bf16 v[80:83], v[132:135], v[178:181], v[80:83]
	v_mfma_f32_16x16x32_bf16 v[76:79], v[168:171], v[178:181], v[76:79]
	v_mfma_f32_16x16x32_bf16 v[72:75], v[132:135], v[186:189], v[72:75]
	v_mfma_f32_16x16x32_bf16 v[68:71], v[168:171], v[186:189], v[68:71]
	v_mfma_f32_16x16x32_bf16 v[64:67], v[132:135], v[202:205], v[64:67]
	v_mfma_f32_16x16x32_bf16 v[60:63], v[168:171], v[202:205], v[60:63]
	v_mfma_f32_16x16x32_bf16 v[56:59], v[132:135], v[210:213], v[56:59]
	v_mfma_f32_16x16x32_bf16 v[52:55], v[168:171], v[210:213], v[52:55]
	v_mfma_f32_16x16x32_bf16 v[80:83], v[164:167], v[182:185], v[80:83]
	v_mfma_f32_16x16x32_bf16 v[76:79], v[174:177], v[182:185], v[76:79]
	v_mfma_f32_16x16x32_bf16 v[72:75], v[164:167], v[190:193], v[72:75]
	v_mfma_f32_16x16x32_bf16 v[68:71], v[174:177], v[190:193], v[68:71]
	v_mfma_f32_16x16x32_bf16 v[64:67], v[164:167], v[206:209], v[64:67]
	v_mfma_f32_16x16x32_bf16 v[60:63], v[174:177], v[206:209], v[60:63]
	v_mfma_f32_16x16x32_bf16 v[56:59], v[164:167], v[214:217], v[56:59]
	v_mfma_f32_16x16x32_bf16 v[52:55], v[174:177], v[214:217], v[52:55]
	s_barrier
	s_add_u32 s30, s46, 0xc0080
	s_addc_u32 s31, s47, 0
	s_add_i32 s27, s36, s52
	v_lshl_add_u64 v[0:1], s[30:31], 0, v[138:139]
	s_mov_b32 m0, s27
	s_nop 0
	global_load_lds_dwordx4 v[0:1], off
	v_lshl_add_u64 v[0:1], s[30:31], 0, v[142:143]
	s_add_i32 m0, s27, 0x2000
	s_nop 0
	global_load_lds_dwordx4 v[0:1], off
	s_waitcnt vmcnt(6)
	s_barrier
	v_mfma_f32_16x16x32_bf16 v[48:51], v[236:239], v[178:181], v[48:51]
	v_mfma_f32_16x16x32_bf16 v[44:47], v[244:247], v[178:181], v[44:47]
	v_mfma_f32_16x16x32_bf16 v[40:43], v[236:239], v[186:189], v[40:43]
	v_mfma_f32_16x16x32_bf16 v[36:39], v[244:247], v[186:189], v[36:39]
	v_mfma_f32_16x16x32_bf16 v[32:35], v[236:239], v[202:205], v[32:35]
	v_mfma_f32_16x16x32_bf16 v[28:31], v[244:247], v[202:205], v[28:31]
	v_mfma_f32_16x16x32_bf16 v[24:27], v[236:239], v[210:213], v[24:27]
	v_mfma_f32_16x16x32_bf16 v[20:23], v[244:247], v[210:213], v[20:23]
	v_mfma_f32_16x16x32_bf16 v[48:51], v[240:243], v[182:185], v[48:51]
	v_mfma_f32_16x16x32_bf16 v[44:47], v[248:251], v[182:185], v[44:47]
	v_mfma_f32_16x16x32_bf16 v[40:43], v[240:243], v[190:193], v[40:43]
	v_mfma_f32_16x16x32_bf16 v[36:39], v[248:251], v[190:193], v[36:39]
	v_mfma_f32_16x16x32_bf16 v[32:35], v[240:243], v[206:209], v[32:35]
	v_mfma_f32_16x16x32_bf16 v[28:31], v[248:251], v[206:209], v[28:31]
	v_mfma_f32_16x16x32_bf16 v[24:27], v[240:243], v[214:217], v[24:27]
	v_mfma_f32_16x16x32_bf16 v[20:23], v[248:251], v[214:217], v[20:23]
	s_add_u32 s24, s24, 0x100
	s_addc_u32 s25, s25, 0
	s_cmp_ge_i32 s26, s22
	s_mov_b64 s[40:41], s[44:45]
	s_mov_b32 s27, s26
	s_barrier
	s_cbranch_scc0 .LBB0_175
	s_lshl_b32 s46, s66, 8
	v_lshl_or_b32 v0, s20, 8, v159
	s_mov_b32 s44, 0xbfb8aa3b
	s_mov_b32 s45, 0xbfb8aa3b
	v_lshlrev_b32_e32 v0, 1, v0
	v_add_u32_e32 v0, 0x1000, v0
	s_cmp_lg_u32 s21, 1
	s_cbranch_scc0 .Lg2_kind1
	v_readlane_b32 s22, v252, 34
	v_readlane_b32 s23, v252, 35
	v_add_u32_e32 v2, s46, v144
	v_mad_u32_u24 v2, v2, s29, v0
	global_load_dwordx4 v[132:135], v2, s[96:97] offset:2048
	v_add_u32_e32 v2, s46, v144
	v_mad_u32_u24 v2, v2, s29, v0
	global_load_dwordx4 v[178:181], v2, s[96:97] offset:2304
	v_add_u32_e32 v2, s46, v146
	v_mad_u32_u24 v2, v2, s29, v0
	global_load_dwordx4 v[182:185], v2, s[96:97] offset:2048
	v_add_u32_e32 v2, s46, v146
	v_mad_u32_u24 v2, v2, s29, v0
	global_load_dwordx4 v[186:189], v2, s[96:97] offset:2304
	v_add_u32_e32 v2, s46, v148
	v_mad_u32_u24 v2, v2, s29, v0
	global_load_dwordx4 v[190:193], v2, s[96:97] offset:2048
	v_add_u32_e32 v2, s46, v148
	v_mad_u32_u24 v2, v2, s29, v0
	global_load_dwordx4 v[202:205], v2, s[96:97] offset:2304
	v_add_u32_e32 v2, s46, v150
	v_mad_u32_u24 v2, v2, s29, v0
	global_load_dwordx4 v[206:209], v2, s[96:97] offset:2048
	v_add_u32_e32 v2, s46, v150
	v_mad_u32_u24 v2, v2, s29, v0
	global_load_dwordx4 v[210:213], v2, s[96:97] offset:2304
	v_add_u32_e32 v2, s46, v152
	v_mad_u32_u24 v2, v2, s29, v0
	global_load_dwordx4 v[214:217], v2, s[96:97] offset:2048
	v_add_u32_e32 v2, s46, v152
	v_mad_u32_u24 v2, v2, s29, v0
	global_load_dwordx4 v[236:239], v2, s[96:97] offset:2304
	v_add_u32_e32 v2, s46, v154
	v_mad_u32_u24 v2, v2, s29, v0
	global_load_dwordx4 v[240:243], v2, s[96:97] offset:2048
	v_add_u32_e32 v2, s46, v154
	v_mad_u32_u24 v2, v2, s29, v0
	global_load_dwordx4 v[244:247], v2, s[96:97] offset:2304
	v_add_u32_e32 v2, s46, v156
	v_mad_u32_u24 v2, v2, s29, v0
	global_load_dwordx4 v[248:251], v2, s[96:97] offset:2048
	s_waitcnt vmcnt(12)
	v_lshlrev_b32_e32 v164, 16, v132
	v_and_b32_e32 v165, 0xffff0000, v132
	v_lshlrev_b32_e32 v166, 16, v133
	v_and_b32_e32 v167, 0xffff0000, v133
	v_lshlrev_b32_e32 v168, 16, v134
	v_and_b32_e32 v169, 0xffff0000, v134
	v_lshlrev_b32_e32 v170, 16, v135
	v_and_b32_e32 v171, 0xffff0000, v135
	v_add_u32_e32 v2, s46, v156
	v_mad_u32_u24 v2, v2, s29, v0
	global_load_dwordx4 v[132:135], v2, s[96:97] offset:2304
	v_add_u32_e32 v1, s46, v144
	v_lshl_add_u32 v1, v1, 11, v0
	v_med3_f32 v164, v164, s34, v227
	v_med3_f32 v165, v165, s34, v227
	v_med3_f32 v166, v166, s34, v227
	v_med3_f32 v167, v167, s34, v227
	v_med3_f32 v168, v168, s34, v227
	v_med3_f32 v169, v169, s34, v227
	v_med3_f32 v170, v170, s34, v227
	v_med3_f32 v171, v171, s34, v227
	v_pk_mul_f32 v[164:165], v[164:165], s[44:45]
	v_pk_mul_f32 v[166:167], v[166:167], s[44:45]
	v_pk_mul_f32 v[168:169], v[168:169], s[44:45]
	v_pk_mul_f32 v[170:171], v[170:171], s[44:45]
	v_exp_f32_e32 v164, v164
	v_exp_f32_e32 v165, v165
	v_exp_f32_e32 v166, v166
	v_exp_f32_e32 v167, v167
	v_exp_f32_e32 v168, v168
	v_exp_f32_e32 v169, v169
	v_exp_f32_e32 v170, v170
	v_exp_f32_e32 v171, v171
	v_pk_add_f32 v[164:165], v[164:165], 1.0 op_sel_hi:[1,0]
	v_pk_add_f32 v[166:167], v[166:167], 1.0 op_sel_hi:[1,0]
	v_pk_add_f32 v[168:169], v[168:169], 1.0 op_sel_hi:[1,0]
	v_pk_add_f32 v[170:171], v[170:171], 1.0 op_sel_hi:[1,0]
	v_rcp_f32_e32 v164, v164
	v_rcp_f32_e32 v165, v165
	v_rcp_f32_e32 v166, v166
	v_rcp_f32_e32 v167, v167
	v_rcp_f32_e32 v168, v168
	v_rcp_f32_e32 v169, v169
	v_rcp_f32_e32 v170, v170
	v_rcp_f32_e32 v171, v171
	v_pk_mul_f32 v[164:165], v[4:5], v[164:165]
	v_pk_mul_f32 v[166:167], v[6:7], v[166:167]
	v_pk_mul_f32 v[168:169], v[8:9], v[168:169]
	v_pk_mul_f32 v[170:171], v[10:11], v[170:171]
	v_cvt_pk_bf16_f32 v174, v164, v165
	v_cvt_pk_bf16_f32 v175, v166, v167
	v_cvt_pk_bf16_f32 v176, v168, v169
	v_cvt_pk_bf16_f32 v177, v170, v171
	global_store_dwordx4 v1, v[174:177], s[22:23] offset:-4096
	s_waitcnt vmcnt(13)
	v_lshlrev_b32_e32 v164, 16, v178
	v_and_b32_e32 v165, 0xffff0000, v178
	v_lshlrev_b32_e32 v166, 16, v179
	v_and_b32_e32 v167, 0xffff0000, v179
	v_lshlrev_b32_e32 v168, 16, v180
	v_and_b32_e32 v169, 0xffff0000, v180
	v_lshlrev_b32_e32 v170, 16, v181
	v_and_b32_e32 v171, 0xffff0000, v181
	v_add_u32_e32 v2, s46, v158
	v_mad_u32_u24 v2, v2, s29, v0
	global_load_dwordx4 v[178:181], v2, s[96:97] offset:2048
	v_med3_f32 v164, v164, s34, v227
	v_med3_f32 v165, v165, s34, v227
	v_med3_f32 v166, v166, s34, v227
	v_med3_f32 v167, v167, s34, v227
	v_med3_f32 v168, v168, s34, v227
	v_med3_f32 v169, v169, s34, v227
	v_med3_f32 v170, v170, s34, v227
	v_med3_f32 v171, v171, s34, v227
	v_pk_mul_f32 v[164:165], v[164:165], s[44:45]
	v_pk_mul_f32 v[166:167], v[166:167], s[44:45]
	v_pk_mul_f32 v[168:169], v[168:169], s[44:45]
	v_pk_mul_f32 v[170:171], v[170:171], s[44:45]
	v_exp_f32_e32 v164, v164
	v_exp_f32_e32 v165, v165
	v_exp_f32_e32 v166, v166
	v_exp_f32_e32 v167, v167
	v_exp_f32_e32 v168, v168
	v_exp_f32_e32 v169, v169
	v_exp_f32_e32 v170, v170
	v_exp_f32_e32 v171, v171
	v_pk_add_f32 v[164:165], v[164:165], 1.0 op_sel_hi:[1,0]
	v_pk_add_f32 v[166:167], v[166:167], 1.0 op_sel_hi:[1,0]
	v_pk_add_f32 v[168:169], v[168:169], 1.0 op_sel_hi:[1,0]
	v_pk_add_f32 v[170:171], v[170:171], 1.0 op_sel_hi:[1,0]
	v_rcp_f32_e32 v164, v164
	v_rcp_f32_e32 v165, v165
	v_rcp_f32_e32 v166, v166
	v_rcp_f32_e32 v167, v167
	v_rcp_f32_e32 v168, v168
	v_rcp_f32_e32 v169, v169
	v_rcp_f32_e32 v170, v170
	v_rcp_f32_e32 v171, v171
	v_pk_mul_f32 v[164:165], v[12:13], v[164:165]
	v_pk_mul_f32 v[166:167], v[14:15], v[166:167]
	v_pk_mul_f32 v[168:169], v[16:17], v[168:169]
	v_pk_mul_f32 v[170:171], v[18:19], v[170:171]
	v_cvt_pk_bf16_f32 v174, v164, v165
	v_cvt_pk_bf16_f32 v175, v166, v167
	v_cvt_pk_bf16_f32 v176, v168, v169
	v_cvt_pk_bf16_f32 v177, v170, v171
	global_store_dwordx4 v1, v[174:177], s[22:23] offset:-3840
	s_waitcnt vmcnt(14)
	v_lshlrev_b32_e32 v164, 16, v182
	v_and_b32_e32 v165, 0xffff0000, v182
	v_lshlrev_b32_e32 v166, 16, v183
	v_and_b32_e32 v167, 0xffff0000, v183
	v_lshlrev_b32_e32 v168, 16, v184
	v_and_b32_e32 v169, 0xffff0000, v184
	v_lshlrev_b32_e32 v170, 16, v185
	v_and_b32_e32 v171, 0xffff0000, v185
	v_add_u32_e32 v2, s46, v158
	v_mad_u32_u24 v2, v2, s29, v0
	global_load_dwordx4 v[182:185], v2, s[96:97] offset:2304
	v_add_u32_e32 v1, s46, v146
	v_lshl_add_u32 v1, v1, 11, v0
	v_med3_f32 v164, v164, s34, v227
	v_med3_f32 v165, v165, s34, v227
	v_med3_f32 v166, v166, s34, v227
	v_med3_f32 v167, v167, s34, v227
	v_med3_f32 v168, v168, s34, v227
	v_med3_f32 v169, v169, s34, v227
	v_med3_f32 v170, v170, s34, v227
	v_med3_f32 v171, v171, s34, v227
	v_pk_mul_f32 v[164:165], v[164:165], s[44:45]
	v_pk_mul_f32 v[166:167], v[166:167], s[44:45]
	v_pk_mul_f32 v[168:169], v[168:169], s[44:45]
	v_pk_mul_f32 v[170:171], v[170:171], s[44:45]
	v_exp_f32_e32 v164, v164
	v_exp_f32_e32 v165, v165
	v_exp_f32_e32 v166, v166
	v_exp_f32_e32 v167, v167
	v_exp_f32_e32 v168, v168
	v_exp_f32_e32 v169, v169
	v_exp_f32_e32 v170, v170
	v_exp_f32_e32 v171, v171
	v_pk_add_f32 v[164:165], v[164:165], 1.0 op_sel_hi:[1,0]
	v_pk_add_f32 v[166:167], v[166:167], 1.0 op_sel_hi:[1,0]
	v_pk_add_f32 v[168:169], v[168:169], 1.0 op_sel_hi:[1,0]
	v_pk_add_f32 v[170:171], v[170:171], 1.0 op_sel_hi:[1,0]
	v_rcp_f32_e32 v164, v164
	v_rcp_f32_e32 v165, v165
	v_rcp_f32_e32 v166, v166
	v_rcp_f32_e32 v167, v167
	v_rcp_f32_e32 v168, v168
	v_rcp_f32_e32 v169, v169
	v_rcp_f32_e32 v170, v170
	v_rcp_f32_e32 v171, v171
	v_pk_mul_f32 v[164:165], v[128:129], v[164:165]
	v_pk_mul_f32 v[166:167], v[130:131], v[166:167]
	v_pk_mul_f32 v[168:169], v[124:125], v[168:169]
	v_pk_mul_f32 v[170:171], v[126:127], v[170:171]
	v_cvt_pk_bf16_f32 v174, v164, v165
	v_cvt_pk_bf16_f32 v175, v166, v167
	v_cvt_pk_bf16_f32 v176, v168, v169
	v_cvt_pk_bf16_f32 v177, v170, v171
	global_store_dwordx4 v1, v[174:177], s[22:23] offset:-4096
	s_waitcnt vmcnt(15)
	v_lshlrev_b32_e32 v164, 16, v186
	v_and_b32_e32 v165, 0xffff0000, v186
	v_lshlrev_b32_e32 v166, 16, v187
	v_and_b32_e32 v167, 0xffff0000, v187
	v_lshlrev_b32_e32 v168, 16, v188
	v_and_b32_e32 v169, 0xffff0000, v188
	v_lshlrev_b32_e32 v170, 16, v189
	v_and_b32_e32 v171, 0xffff0000, v189
	v_med3_f32 v164, v164, s34, v227
	v_med3_f32 v165, v165, s34, v227
	v_med3_f32 v166, v166, s34, v227
	v_med3_f32 v167, v167, s34, v227
	v_med3_f32 v168, v168, s34, v227
	v_med3_f32 v169, v169, s34, v227
	v_med3_f32 v170, v170, s34, v227
	v_med3_f32 v171, v171, s34, v227
	v_pk_mul_f32 v[164:165], v[164:165], s[44:45]
	v_pk_mul_f32 v[166:167], v[166:167], s[44:45]
	v_pk_mul_f32 v[168:169], v[168:169], s[44:45]
	v_pk_mul_f32 v[170:171], v[170:171], s[44:45]
	v_exp_f32_e32 v164, v164
	v_exp_f32_e32 v165, v165
	v_exp_f32_e32 v166, v166
	v_exp_f32_e32 v167, v167
	v_exp_f32_e32 v168, v168
	v_exp_f32_e32 v169, v169
	v_exp_f32_e32 v170, v170
	v_exp_f32_e32 v171, v171
	v_pk_add_f32 v[164:165], v[164:165], 1.0 op_sel_hi:[1,0]
	v_pk_add_f32 v[166:167], v[166:167], 1.0 op_sel_hi:[1,0]
	v_pk_add_f32 v[168:169], v[168:169], 1.0 op_sel_hi:[1,0]
	v_pk_add_f32 v[170:171], v[170:171], 1.0 op_sel_hi:[1,0]
	v_rcp_f32_e32 v164, v164
	v_rcp_f32_e32 v165, v165
	v_rcp_f32_e32 v166, v166
	v_rcp_f32_e32 v167, v167
	v_rcp_f32_e32 v168, v168
	v_rcp_f32_e32 v169, v169
	v_rcp_f32_e32 v170, v170
	v_rcp_f32_e32 v171, v171
	v_pk_mul_f32 v[164:165], v[104:105], v[164:165]
	v_pk_mul_f32 v[166:167], v[106:107], v[166:167]
	v_pk_mul_f32 v[168:169], v[100:101], v[168:169]
	v_pk_mul_f32 v[170:171], v[102:103], v[170:171]
	v_cvt_pk_bf16_f32 v174, v164, v165
	v_cvt_pk_bf16_f32 v175, v166, v167
	v_cvt_pk_bf16_f32 v176, v168, v169
	v_cvt_pk_bf16_f32 v177, v170, v171
	global_store_dwordx4 v1, v[174:177], s[22:23] offset:-3840
	s_waitcnt vmcnt(15)
	v_lshlrev_b32_e32 v164, 16, v190
	v_and_b32_e32 v165, 0xffff0000, v190
	v_lshlrev_b32_e32 v166, 16, v191
	v_and_b32_e32 v167, 0xffff0000, v191
	v_lshlrev_b32_e32 v168, 16, v192
	v_and_b32_e32 v169, 0xffff0000, v192
	v_lshlrev_b32_e32 v170, 16, v193
	v_and_b32_e32 v171, 0xffff0000, v193
	v_add_u32_e32 v1, s46, v148
	v_lshl_add_u32 v1, v1, 11, v0
	v_med3_f32 v164, v164, s34, v227
	v_med3_f32 v165, v165, s34, v227
	v_med3_f32 v166, v166, s34, v227
	v_med3_f32 v167, v167, s34, v227
	v_med3_f32 v168, v168, s34, v227
	v_med3_f32 v169, v169, s34, v227
	v_med3_f32 v170, v170, s34, v227
	v_med3_f32 v171, v171, s34, v227
	v_pk_mul_f32 v[164:165], v[164:165], s[44:45]
	v_pk_mul_f32 v[166:167], v[166:167], s[44:45]
	v_pk_mul_f32 v[168:169], v[168:169], s[44:45]
	v_pk_mul_f32 v[170:171], v[170:171], s[44:45]
	v_exp_f32_e32 v164, v164
	v_exp_f32_e32 v165, v165
	v_exp_f32_e32 v166, v166
	v_exp_f32_e32 v167, v167
	v_exp_f32_e32 v168, v168
	v_exp_f32_e32 v169, v169
	v_exp_f32_e32 v170, v170
	v_exp_f32_e32 v171, v171
	v_pk_add_f32 v[164:165], v[164:165], 1.0 op_sel_hi:[1,0]
	v_pk_add_f32 v[166:167], v[166:167], 1.0 op_sel_hi:[1,0]
	v_pk_add_f32 v[168:169], v[168:169], 1.0 op_sel_hi:[1,0]
	v_pk_add_f32 v[170:171], v[170:171], 1.0 op_sel_hi:[1,0]
	v_rcp_f32_e32 v164, v164
	v_rcp_f32_e32 v165, v165
	v_rcp_f32_e32 v166, v166
	v_rcp_f32_e32 v167, v167
	v_rcp_f32_e32 v168, v168
	v_rcp_f32_e32 v169, v169
	v_rcp_f32_e32 v170, v170
	v_rcp_f32_e32 v171, v171
	v_pk_mul_f32 v[164:165], v[120:121], v[164:165]
	v_pk_mul_f32 v[166:167], v[122:123], v[166:167]
	v_pk_mul_f32 v[168:169], v[116:117], v[168:169]
	v_pk_mul_f32 v[170:171], v[118:119], v[170:171]
	v_cvt_pk_bf16_f32 v174, v164, v165
	v_cvt_pk_bf16_f32 v175, v166, v167
	v_cvt_pk_bf16_f32 v176, v168, v169
	v_cvt_pk_bf16_f32 v177, v170, v171
	global_store_dwordx4 v1, v[174:177], s[22:23] offset:-4096
	s_waitcnt vmcnt(15)
	v_lshlrev_b32_e32 v164, 16, v202
	v_and_b32_e32 v165, 0xffff0000, v202
	v_lshlrev_b32_e32 v166, 16, v203
	v_and_b32_e32 v167, 0xffff0000, v203
	v_lshlrev_b32_e32 v168, 16, v204
	v_and_b32_e32 v169, 0xffff0000, v204
	v_lshlrev_b32_e32 v170, 16, v205
	v_and_b32_e32 v171, 0xffff0000, v205
	v_med3_f32 v164, v164, s34, v227
	v_med3_f32 v165, v165, s34, v227
	v_med3_f32 v166, v166, s34, v227
	v_med3_f32 v167, v167, s34, v227
	v_med3_f32 v168, v168, s34, v227
	v_med3_f32 v169, v169, s34, v227
	v_med3_f32 v170, v170, s34, v227
	v_med3_f32 v171, v171, s34, v227
	v_pk_mul_f32 v[164:165], v[164:165], s[44:45]
	v_pk_mul_f32 v[166:167], v[166:167], s[44:45]
	v_pk_mul_f32 v[168:169], v[168:169], s[44:45]
	v_pk_mul_f32 v[170:171], v[170:171], s[44:45]
	v_exp_f32_e32 v164, v164
	v_exp_f32_e32 v165, v165
	v_exp_f32_e32 v166, v166
	v_exp_f32_e32 v167, v167
	v_exp_f32_e32 v168, v168
	v_exp_f32_e32 v169, v169
	v_exp_f32_e32 v170, v170
	v_exp_f32_e32 v171, v171
	v_pk_add_f32 v[164:165], v[164:165], 1.0 op_sel_hi:[1,0]
	v_pk_add_f32 v[166:167], v[166:167], 1.0 op_sel_hi:[1,0]
	v_pk_add_f32 v[168:169], v[168:169], 1.0 op_sel_hi:[1,0]
	v_pk_add_f32 v[170:171], v[170:171], 1.0 op_sel_hi:[1,0]
	v_rcp_f32_e32 v164, v164
	v_rcp_f32_e32 v165, v165
	v_rcp_f32_e32 v166, v166
	v_rcp_f32_e32 v167, v167
	v_rcp_f32_e32 v168, v168
	v_rcp_f32_e32 v169, v169
	v_rcp_f32_e32 v170, v170
	v_rcp_f32_e32 v171, v171
	v_pk_mul_f32 v[164:165], v[96:97], v[164:165]
	v_pk_mul_f32 v[166:167], v[98:99], v[166:167]
	v_pk_mul_f32 v[168:169], v[92:93], v[168:169]
	v_pk_mul_f32 v[170:171], v[94:95], v[170:171]
	v_cvt_pk_bf16_f32 v174, v164, v165
	v_cvt_pk_bf16_f32 v175, v166, v167
	v_cvt_pk_bf16_f32 v176, v168, v169
	v_cvt_pk_bf16_f32 v177, v170, v171
	global_store_dwordx4 v1, v[174:177], s[22:23] offset:-3840
	s_waitcnt vmcnt(15)
	v_lshlrev_b32_e32 v164, 16, v206
	v_and_b32_e32 v165, 0xffff0000, v206
	v_lshlrev_b32_e32 v166, 16, v207
	v_and_b32_e32 v167, 0xffff0000, v207
	v_lshlrev_b32_e32 v168, 16, v208
	v_and_b32_e32 v169, 0xffff0000, v208
	v_lshlrev_b32_e32 v170, 16, v209
	v_and_b32_e32 v171, 0xffff0000, v209
	v_add_u32_e32 v1, s46, v150
	v_lshl_add_u32 v1, v1, 11, v0
	v_med3_f32 v164, v164, s34, v227
	v_med3_f32 v165, v165, s34, v227
	v_med3_f32 v166, v166, s34, v227
	v_med3_f32 v167, v167, s34, v227
	v_med3_f32 v168, v168, s34, v227
	v_med3_f32 v169, v169, s34, v227
	v_med3_f32 v170, v170, s34, v227
	v_med3_f32 v171, v171, s34, v227
	v_pk_mul_f32 v[164:165], v[164:165], s[44:45]
	v_pk_mul_f32 v[166:167], v[166:167], s[44:45]
	v_pk_mul_f32 v[168:169], v[168:169], s[44:45]
	v_pk_mul_f32 v[170:171], v[170:171], s[44:45]
	v_exp_f32_e32 v164, v164
	v_exp_f32_e32 v165, v165
	v_exp_f32_e32 v166, v166
	v_exp_f32_e32 v167, v167
	v_exp_f32_e32 v168, v168
	v_exp_f32_e32 v169, v169
	v_exp_f32_e32 v170, v170
	v_exp_f32_e32 v171, v171
	v_pk_add_f32 v[164:165], v[164:165], 1.0 op_sel_hi:[1,0]
	v_pk_add_f32 v[166:167], v[166:167], 1.0 op_sel_hi:[1,0]
	v_pk_add_f32 v[168:169], v[168:169], 1.0 op_sel_hi:[1,0]
	v_pk_add_f32 v[170:171], v[170:171], 1.0 op_sel_hi:[1,0]
	v_rcp_f32_e32 v164, v164
	v_rcp_f32_e32 v165, v165
	v_rcp_f32_e32 v166, v166
	v_rcp_f32_e32 v167, v167
	v_rcp_f32_e32 v168, v168
	v_rcp_f32_e32 v169, v169
	v_rcp_f32_e32 v170, v170
	v_rcp_f32_e32 v171, v171
	v_pk_mul_f32 v[164:165], v[112:113], v[164:165]
	v_pk_mul_f32 v[166:167], v[114:115], v[166:167]
	v_pk_mul_f32 v[168:169], v[108:109], v[168:169]
	v_pk_mul_f32 v[170:171], v[110:111], v[170:171]
	v_cvt_pk_bf16_f32 v174, v164, v165
	v_cvt_pk_bf16_f32 v175, v166, v167
	v_cvt_pk_bf16_f32 v176, v168, v169
	v_cvt_pk_bf16_f32 v177, v170, v171
	global_store_dwordx4 v1, v[174:177], s[22:23] offset:-4096
	s_waitcnt vmcnt(15)
	v_lshlrev_b32_e32 v164, 16, v210
	v_and_b32_e32 v165, 0xffff0000, v210
	v_lshlrev_b32_e32 v166, 16, v211
	v_and_b32_e32 v167, 0xffff0000, v211
	v_lshlrev_b32_e32 v168, 16, v212
	v_and_b32_e32 v169, 0xffff0000, v212
	v_lshlrev_b32_e32 v170, 16, v213
	v_and_b32_e32 v171, 0xffff0000, v213
	v_med3_f32 v164, v164, s34, v227
	v_med3_f32 v165, v165, s34, v227
	v_med3_f32 v166, v166, s34, v227
	v_med3_f32 v167, v167, s34, v227
	v_med3_f32 v168, v168, s34, v227
	v_med3_f32 v169, v169, s34, v227
	v_med3_f32 v170, v170, s34, v227
	v_med3_f32 v171, v171, s34, v227
	v_pk_mul_f32 v[164:165], v[164:165], s[44:45]
	v_pk_mul_f32 v[166:167], v[166:167], s[44:45]
	v_pk_mul_f32 v[168:169], v[168:169], s[44:45]
	v_pk_mul_f32 v[170:171], v[170:171], s[44:45]
	v_exp_f32_e32 v164, v164
	v_exp_f32_e32 v165, v165
	v_exp_f32_e32 v166, v166
	v_exp_f32_e32 v167, v167
	v_exp_f32_e32 v168, v168
	v_exp_f32_e32 v169, v169
	v_exp_f32_e32 v170, v170
	v_exp_f32_e32 v171, v171
	v_pk_add_f32 v[164:165], v[164:165], 1.0 op_sel_hi:[1,0]
	v_pk_add_f32 v[166:167], v[166:167], 1.0 op_sel_hi:[1,0]
	v_pk_add_f32 v[168:169], v[168:169], 1.0 op_sel_hi:[1,0]
	v_pk_add_f32 v[170:171], v[170:171], 1.0 op_sel_hi:[1,0]
	v_rcp_f32_e32 v164, v164
	v_rcp_f32_e32 v165, v165
	v_rcp_f32_e32 v166, v166
	v_rcp_f32_e32 v167, v167
	v_rcp_f32_e32 v168, v168
	v_rcp_f32_e32 v169, v169
	v_rcp_f32_e32 v170, v170
	v_rcp_f32_e32 v171, v171
	v_pk_mul_f32 v[164:165], v[88:89], v[164:165]
	v_pk_mul_f32 v[166:167], v[90:91], v[166:167]
	v_pk_mul_f32 v[168:169], v[84:85], v[168:169]
	v_pk_mul_f32 v[170:171], v[86:87], v[170:171]
	v_cvt_pk_bf16_f32 v174, v164, v165
	v_cvt_pk_bf16_f32 v175, v166, v167
	v_cvt_pk_bf16_f32 v176, v168, v169
	v_cvt_pk_bf16_f32 v177, v170, v171
	global_store_dwordx4 v1, v[174:177], s[22:23] offset:-3840
	s_waitcnt vmcnt(15)
	v_lshlrev_b32_e32 v164, 16, v214
	v_and_b32_e32 v165, 0xffff0000, v214
	v_lshlrev_b32_e32 v166, 16, v215
	v_and_b32_e32 v167, 0xffff0000, v215
	v_lshlrev_b32_e32 v168, 16, v216
	v_and_b32_e32 v169, 0xffff0000, v216
	v_lshlrev_b32_e32 v170, 16, v217
	v_and_b32_e32 v171, 0xffff0000, v217
	v_add_u32_e32 v1, s46, v152
	v_lshl_add_u32 v1, v1, 11, v0
	v_med3_f32 v164, v164, s34, v227
	v_med3_f32 v165, v165, s34, v227
	v_med3_f32 v166, v166, s34, v227
	v_med3_f32 v167, v167, s34, v227
	v_med3_f32 v168, v168, s34, v227
	v_med3_f32 v169, v169, s34, v227
	v_med3_f32 v170, v170, s34, v227
	v_med3_f32 v171, v171, s34, v227
	v_pk_mul_f32 v[164:165], v[164:165], s[44:45]
	v_pk_mul_f32 v[166:167], v[166:167], s[44:45]
	v_pk_mul_f32 v[168:169], v[168:169], s[44:45]
	v_pk_mul_f32 v[170:171], v[170:171], s[44:45]
	v_exp_f32_e32 v164, v164
	v_exp_f32_e32 v165, v165
	v_exp_f32_e32 v166, v166
	v_exp_f32_e32 v167, v167
	v_exp_f32_e32 v168, v168
	v_exp_f32_e32 v169, v169
	v_exp_f32_e32 v170, v170
	v_exp_f32_e32 v171, v171
	v_pk_add_f32 v[164:165], v[164:165], 1.0 op_sel_hi:[1,0]
	v_pk_add_f32 v[166:167], v[166:167], 1.0 op_sel_hi:[1,0]
	v_pk_add_f32 v[168:169], v[168:169], 1.0 op_sel_hi:[1,0]
	v_pk_add_f32 v[170:171], v[170:171], 1.0 op_sel_hi:[1,0]
	v_rcp_f32_e32 v164, v164
	v_rcp_f32_e32 v165, v165
	v_rcp_f32_e32 v166, v166
	v_rcp_f32_e32 v167, v167
	v_rcp_f32_e32 v168, v168
	v_rcp_f32_e32 v169, v169
	v_rcp_f32_e32 v170, v170
	v_rcp_f32_e32 v171, v171
	v_pk_mul_f32 v[164:165], v[80:81], v[164:165]
	v_pk_mul_f32 v[166:167], v[82:83], v[166:167]
	v_pk_mul_f32 v[168:169], v[76:77], v[168:169]
	v_pk_mul_f32 v[170:171], v[78:79], v[170:171]
	v_cvt_pk_bf16_f32 v174, v164, v165
	v_cvt_pk_bf16_f32 v175, v166, v167
	v_cvt_pk_bf16_f32 v176, v168, v169
	v_cvt_pk_bf16_f32 v177, v170, v171
	global_store_dwordx4 v1, v[174:177], s[22:23] offset:-4096
	s_waitcnt vmcnt(15)
	v_lshlrev_b32_e32 v164, 16, v236
	v_and_b32_e32 v165, 0xffff0000, v236
	v_lshlrev_b32_e32 v166, 16, v237
	v_and_b32_e32 v167, 0xffff0000, v237
	v_lshlrev_b32_e32 v168, 16, v238
	v_and_b32_e32 v169, 0xffff0000, v238
	v_lshlrev_b32_e32 v170, 16, v239
	v_and_b32_e32 v171, 0xffff0000, v239
	v_med3_f32 v164, v164, s34, v227
	v_med3_f32 v165, v165, s34, v227
	v_med3_f32 v166, v166, s34, v227
	v_med3_f32 v167, v167, s34, v227
	v_med3_f32 v168, v168, s34, v227
	v_med3_f32 v169, v169, s34, v227
	v_med3_f32 v170, v170, s34, v227
	v_med3_f32 v171, v171, s34, v227
	v_pk_mul_f32 v[164:165], v[164:165], s[44:45]
	v_pk_mul_f32 v[166:167], v[166:167], s[44:45]
	v_pk_mul_f32 v[168:169], v[168:169], s[44:45]
	v_pk_mul_f32 v[170:171], v[170:171], s[44:45]
	v_exp_f32_e32 v164, v164
	v_exp_f32_e32 v165, v165
	v_exp_f32_e32 v166, v166
	v_exp_f32_e32 v167, v167
	v_exp_f32_e32 v168, v168
	v_exp_f32_e32 v169, v169
	v_exp_f32_e32 v170, v170
	v_exp_f32_e32 v171, v171
	v_pk_add_f32 v[164:165], v[164:165], 1.0 op_sel_hi:[1,0]
	v_pk_add_f32 v[166:167], v[166:167], 1.0 op_sel_hi:[1,0]
	v_pk_add_f32 v[168:169], v[168:169], 1.0 op_sel_hi:[1,0]
	v_pk_add_f32 v[170:171], v[170:171], 1.0 op_sel_hi:[1,0]
	v_rcp_f32_e32 v164, v164
	v_rcp_f32_e32 v165, v165
	v_rcp_f32_e32 v166, v166
	v_rcp_f32_e32 v167, v167
	v_rcp_f32_e32 v168, v168
	v_rcp_f32_e32 v169, v169
	v_rcp_f32_e32 v170, v170
	v_rcp_f32_e32 v171, v171
	v_pk_mul_f32 v[164:165], v[48:49], v[164:165]
	v_pk_mul_f32 v[166:167], v[50:51], v[166:167]
	v_pk_mul_f32 v[168:169], v[44:45], v[168:169]
	v_pk_mul_f32 v[170:171], v[46:47], v[170:171]
	v_cvt_pk_bf16_f32 v174, v164, v165
	v_cvt_pk_bf16_f32 v175, v166, v167
	v_cvt_pk_bf16_f32 v176, v168, v169
	v_cvt_pk_bf16_f32 v177, v170, v171
	global_store_dwordx4 v1, v[174:177], s[22:23] offset:-3840
	s_waitcnt vmcnt(15)
	v_lshlrev_b32_e32 v164, 16, v240
	v_and_b32_e32 v165, 0xffff0000, v240
	v_lshlrev_b32_e32 v166, 16, v241
	v_and_b32_e32 v167, 0xffff0000, v241
	v_lshlrev_b32_e32 v168, 16, v242
	v_and_b32_e32 v169, 0xffff0000, v242
	v_lshlrev_b32_e32 v170, 16, v243
	v_and_b32_e32 v171, 0xffff0000, v243
	v_add_u32_e32 v1, s46, v154
	v_lshl_add_u32 v1, v1, 11, v0
	v_med3_f32 v164, v164, s34, v227
	v_med3_f32 v165, v165, s34, v227
	v_med3_f32 v166, v166, s34, v227
	v_med3_f32 v167, v167, s34, v227
	v_med3_f32 v168, v168, s34, v227
	v_med3_f32 v169, v169, s34, v227
	v_med3_f32 v170, v170, s34, v227
	v_med3_f32 v171, v171, s34, v227
	v_pk_mul_f32 v[164:165], v[164:165], s[44:45]
	v_pk_mul_f32 v[166:167], v[166:167], s[44:45]
	v_pk_mul_f32 v[168:169], v[168:169], s[44:45]
	v_pk_mul_f32 v[170:171], v[170:171], s[44:45]
	v_exp_f32_e32 v164, v164
	v_exp_f32_e32 v165, v165
	v_exp_f32_e32 v166, v166
	v_exp_f32_e32 v167, v167
	v_exp_f32_e32 v168, v168
	v_exp_f32_e32 v169, v169
	v_exp_f32_e32 v170, v170
	v_exp_f32_e32 v171, v171
	v_pk_add_f32 v[164:165], v[164:165], 1.0 op_sel_hi:[1,0]
	v_pk_add_f32 v[166:167], v[166:167], 1.0 op_sel_hi:[1,0]
	v_pk_add_f32 v[168:169], v[168:169], 1.0 op_sel_hi:[1,0]
	v_pk_add_f32 v[170:171], v[170:171], 1.0 op_sel_hi:[1,0]
	v_rcp_f32_e32 v164, v164
	v_rcp_f32_e32 v165, v165
	v_rcp_f32_e32 v166, v166
	v_rcp_f32_e32 v167, v167
	v_rcp_f32_e32 v168, v168
	v_rcp_f32_e32 v169, v169
	v_rcp_f32_e32 v170, v170
	v_rcp_f32_e32 v171, v171
	v_pk_mul_f32 v[164:165], v[72:73], v[164:165]
	v_pk_mul_f32 v[166:167], v[74:75], v[166:167]
	v_pk_mul_f32 v[168:169], v[68:69], v[168:169]
	v_pk_mul_f32 v[170:171], v[70:71], v[170:171]
	v_cvt_pk_bf16_f32 v174, v164, v165
	v_cvt_pk_bf16_f32 v175, v166, v167
	v_cvt_pk_bf16_f32 v176, v168, v169
	v_cvt_pk_bf16_f32 v177, v170, v171
	global_store_dwordx4 v1, v[174:177], s[22:23] offset:-4096
	s_waitcnt vmcnt(15)
	v_lshlrev_b32_e32 v164, 16, v244
	v_and_b32_e32 v165, 0xffff0000, v244
	v_lshlrev_b32_e32 v166, 16, v245
	v_and_b32_e32 v167, 0xffff0000, v245
	v_lshlrev_b32_e32 v168, 16, v246
	v_and_b32_e32 v169, 0xffff0000, v246
	v_lshlrev_b32_e32 v170, 16, v247
	v_and_b32_e32 v171, 0xffff0000, v247
	v_med3_f32 v164, v164, s34, v227
	v_med3_f32 v165, v165, s34, v227
	v_med3_f32 v166, v166, s34, v227
	v_med3_f32 v167, v167, s34, v227
	v_med3_f32 v168, v168, s34, v227
	v_med3_f32 v169, v169, s34, v227
	v_med3_f32 v170, v170, s34, v227
	v_med3_f32 v171, v171, s34, v227
	v_pk_mul_f32 v[164:165], v[164:165], s[44:45]
	v_pk_mul_f32 v[166:167], v[166:167], s[44:45]
	v_pk_mul_f32 v[168:169], v[168:169], s[44:45]
	v_pk_mul_f32 v[170:171], v[170:171], s[44:45]
	v_exp_f32_e32 v164, v164
	v_exp_f32_e32 v165, v165
	v_exp_f32_e32 v166, v166
	v_exp_f32_e32 v167, v167
	v_exp_f32_e32 v168, v168
	v_exp_f32_e32 v169, v169
	v_exp_f32_e32 v170, v170
	v_exp_f32_e32 v171, v171
	v_pk_add_f32 v[164:165], v[164:165], 1.0 op_sel_hi:[1,0]
	v_pk_add_f32 v[166:167], v[166:167], 1.0 op_sel_hi:[1,0]
	v_pk_add_f32 v[168:169], v[168:169], 1.0 op_sel_hi:[1,0]
	v_pk_add_f32 v[170:171], v[170:171], 1.0 op_sel_hi:[1,0]
	v_rcp_f32_e32 v164, v164
	v_rcp_f32_e32 v165, v165
	v_rcp_f32_e32 v166, v166
	v_rcp_f32_e32 v167, v167
	v_rcp_f32_e32 v168, v168
	v_rcp_f32_e32 v169, v169
	v_rcp_f32_e32 v170, v170
	v_rcp_f32_e32 v171, v171
	v_pk_mul_f32 v[164:165], v[40:41], v[164:165]
	v_pk_mul_f32 v[166:167], v[42:43], v[166:167]
	v_pk_mul_f32 v[168:169], v[36:37], v[168:169]
	v_pk_mul_f32 v[170:171], v[38:39], v[170:171]
	v_cvt_pk_bf16_f32 v174, v164, v165
	v_cvt_pk_bf16_f32 v175, v166, v167
	v_cvt_pk_bf16_f32 v176, v168, v169
	v_cvt_pk_bf16_f32 v177, v170, v171
	global_store_dwordx4 v1, v[174:177], s[22:23] offset:-3840
	s_waitcnt vmcnt(15)
	v_lshlrev_b32_e32 v164, 16, v248
	v_and_b32_e32 v165, 0xffff0000, v248
	v_lshlrev_b32_e32 v166, 16, v249
	v_and_b32_e32 v167, 0xffff0000, v249
	v_lshlrev_b32_e32 v168, 16, v250
	v_and_b32_e32 v169, 0xffff0000, v250
	v_lshlrev_b32_e32 v170, 16, v251
	v_and_b32_e32 v171, 0xffff0000, v251
	v_add_u32_e32 v1, s46, v156
	v_lshl_add_u32 v1, v1, 11, v0
	v_med3_f32 v164, v164, s34, v227
	v_med3_f32 v165, v165, s34, v227
	v_med3_f32 v166, v166, s34, v227
	v_med3_f32 v167, v167, s34, v227
	v_med3_f32 v168, v168, s34, v227
	v_med3_f32 v169, v169, s34, v227
	v_med3_f32 v170, v170, s34, v227
	v_med3_f32 v171, v171, s34, v227
	v_pk_mul_f32 v[164:165], v[164:165], s[44:45]
	v_pk_mul_f32 v[166:167], v[166:167], s[44:45]
	v_pk_mul_f32 v[168:169], v[168:169], s[44:45]
	v_pk_mul_f32 v[170:171], v[170:171], s[44:45]
	v_exp_f32_e32 v164, v164
	v_exp_f32_e32 v165, v165
	v_exp_f32_e32 v166, v166
	v_exp_f32_e32 v167, v167
	v_exp_f32_e32 v168, v168
	v_exp_f32_e32 v169, v169
	v_exp_f32_e32 v170, v170
	v_exp_f32_e32 v171, v171
	v_pk_add_f32 v[164:165], v[164:165], 1.0 op_sel_hi:[1,0]
	v_pk_add_f32 v[166:167], v[166:167], 1.0 op_sel_hi:[1,0]
	v_pk_add_f32 v[168:169], v[168:169], 1.0 op_sel_hi:[1,0]
	v_pk_add_f32 v[170:171], v[170:171], 1.0 op_sel_hi:[1,0]
	v_rcp_f32_e32 v164, v164
	v_rcp_f32_e32 v165, v165
	v_rcp_f32_e32 v166, v166
	v_rcp_f32_e32 v167, v167
	v_rcp_f32_e32 v168, v168
	v_rcp_f32_e32 v169, v169
	v_rcp_f32_e32 v170, v170
	v_rcp_f32_e32 v171, v171
	v_pk_mul_f32 v[164:165], v[64:65], v[164:165]
	v_pk_mul_f32 v[166:167], v[66:67], v[166:167]
	v_pk_mul_f32 v[168:169], v[60:61], v[168:169]
	v_pk_mul_f32 v[170:171], v[62:63], v[170:171]
	v_cvt_pk_bf16_f32 v174, v164, v165
	v_cvt_pk_bf16_f32 v175, v166, v167
	v_cvt_pk_bf16_f32 v176, v168, v169
	v_cvt_pk_bf16_f32 v177, v170, v171
	global_store_dwordx4 v1, v[174:177], s[22:23] offset:-4096
	s_waitcnt vmcnt(15)
	v_lshlrev_b32_e32 v164, 16, v132
	v_and_b32_e32 v165, 0xffff0000, v132
	v_lshlrev_b32_e32 v166, 16, v133
	v_and_b32_e32 v167, 0xffff0000, v133
	v_lshlrev_b32_e32 v168, 16, v134
	v_and_b32_e32 v169, 0xffff0000, v134
	v_lshlrev_b32_e32 v170, 16, v135
	v_and_b32_e32 v171, 0xffff0000, v135
	v_med3_f32 v164, v164, s34, v227
	v_med3_f32 v165, v165, s34, v227
	v_med3_f32 v166, v166, s34, v227
	v_med3_f32 v167, v167, s34, v227
	v_med3_f32 v168, v168, s34, v227
	v_med3_f32 v169, v169, s34, v227
	v_med3_f32 v170, v170, s34, v227
	v_med3_f32 v171, v171, s34, v227
	v_pk_mul_f32 v[164:165], v[164:165], s[44:45]
	v_pk_mul_f32 v[166:167], v[166:167], s[44:45]
	v_pk_mul_f32 v[168:169], v[168:169], s[44:45]
	v_pk_mul_f32 v[170:171], v[170:171], s[44:45]
	v_exp_f32_e32 v164, v164
	v_exp_f32_e32 v165, v165
	v_exp_f32_e32 v166, v166
	v_exp_f32_e32 v167, v167
	v_exp_f32_e32 v168, v168
	v_exp_f32_e32 v169, v169
	v_exp_f32_e32 v170, v170
	v_exp_f32_e32 v171, v171
	v_pk_add_f32 v[164:165], v[164:165], 1.0 op_sel_hi:[1,0]
	v_pk_add_f32 v[166:167], v[166:167], 1.0 op_sel_hi:[1,0]
	v_pk_add_f32 v[168:169], v[168:169], 1.0 op_sel_hi:[1,0]
	v_pk_add_f32 v[170:171], v[170:171], 1.0 op_sel_hi:[1,0]
	v_rcp_f32_e32 v164, v164
	v_rcp_f32_e32 v165, v165
	v_rcp_f32_e32 v166, v166
	v_rcp_f32_e32 v167, v167
	v_rcp_f32_e32 v168, v168
	v_rcp_f32_e32 v169, v169
	v_rcp_f32_e32 v170, v170
	v_rcp_f32_e32 v171, v171
	v_pk_mul_f32 v[164:165], v[32:33], v[164:165]
	v_pk_mul_f32 v[166:167], v[34:35], v[166:167]
	v_pk_mul_f32 v[168:169], v[28:29], v[168:169]
	v_pk_mul_f32 v[170:171], v[30:31], v[170:171]
	v_cvt_pk_bf16_f32 v174, v164, v165
	v_cvt_pk_bf16_f32 v175, v166, v167
	v_cvt_pk_bf16_f32 v176, v168, v169
	v_cvt_pk_bf16_f32 v177, v170, v171
	global_store_dwordx4 v1, v[174:177], s[22:23] offset:-3840
	s_waitcnt vmcnt(14)
	v_lshlrev_b32_e32 v164, 16, v178
	v_and_b32_e32 v165, 0xffff0000, v178
	v_lshlrev_b32_e32 v166, 16, v179
	v_and_b32_e32 v167, 0xffff0000, v179
	v_lshlrev_b32_e32 v168, 16, v180
	v_and_b32_e32 v169, 0xffff0000, v180
	v_lshlrev_b32_e32 v170, 16, v181
	v_and_b32_e32 v171, 0xffff0000, v181
	v_add_u32_e32 v1, s46, v158
	v_lshl_add_u32 v1, v1, 11, v0
	v_med3_f32 v164, v164, s34, v227
	v_med3_f32 v165, v165, s34, v227
	v_med3_f32 v166, v166, s34, v227
	v_med3_f32 v167, v167, s34, v227
	v_med3_f32 v168, v168, s34, v227
	v_med3_f32 v169, v169, s34, v227
	v_med3_f32 v170, v170, s34, v227
	v_med3_f32 v171, v171, s34, v227
	v_pk_mul_f32 v[164:165], v[164:165], s[44:45]
	v_pk_mul_f32 v[166:167], v[166:167], s[44:45]
	v_pk_mul_f32 v[168:169], v[168:169], s[44:45]
	v_pk_mul_f32 v[170:171], v[170:171], s[44:45]
	v_exp_f32_e32 v164, v164
	v_exp_f32_e32 v165, v165
	v_exp_f32_e32 v166, v166
	v_exp_f32_e32 v167, v167
	v_exp_f32_e32 v168, v168
	v_exp_f32_e32 v169, v169
	v_exp_f32_e32 v170, v170
	v_exp_f32_e32 v171, v171
	v_pk_add_f32 v[164:165], v[164:165], 1.0 op_sel_hi:[1,0]
	v_pk_add_f32 v[166:167], v[166:167], 1.0 op_sel_hi:[1,0]
	v_pk_add_f32 v[168:169], v[168:169], 1.0 op_sel_hi:[1,0]
	v_pk_add_f32 v[170:171], v[170:171], 1.0 op_sel_hi:[1,0]
	v_rcp_f32_e32 v164, v164
	v_rcp_f32_e32 v165, v165
	v_rcp_f32_e32 v166, v166
	v_rcp_f32_e32 v167, v167
	v_rcp_f32_e32 v168, v168
	v_rcp_f32_e32 v169, v169
	v_rcp_f32_e32 v170, v170
	v_rcp_f32_e32 v171, v171
	v_pk_mul_f32 v[164:165], v[56:57], v[164:165]
	v_pk_mul_f32 v[166:167], v[58:59], v[166:167]
	v_pk_mul_f32 v[168:169], v[52:53], v[168:169]
	v_pk_mul_f32 v[170:171], v[54:55], v[170:171]
	v_cvt_pk_bf16_f32 v174, v164, v165
	v_cvt_pk_bf16_f32 v175, v166, v167
	v_cvt_pk_bf16_f32 v176, v168, v169
	v_cvt_pk_bf16_f32 v177, v170, v171
	global_store_dwordx4 v1, v[174:177], s[22:23] offset:-4096
	s_waitcnt vmcnt(13)
	v_lshlrev_b32_e32 v164, 16, v182
	v_and_b32_e32 v165, 0xffff0000, v182
	v_lshlrev_b32_e32 v166, 16, v183
	v_and_b32_e32 v167, 0xffff0000, v183
	v_lshlrev_b32_e32 v168, 16, v184
	v_and_b32_e32 v169, 0xffff0000, v184
	v_lshlrev_b32_e32 v170, 16, v185
	v_and_b32_e32 v171, 0xffff0000, v185
	v_med3_f32 v164, v164, s34, v227
	v_med3_f32 v165, v165, s34, v227
	v_med3_f32 v166, v166, s34, v227
	v_med3_f32 v167, v167, s34, v227
	v_med3_f32 v168, v168, s34, v227
	v_med3_f32 v169, v169, s34, v227
	v_med3_f32 v170, v170, s34, v227
	v_med3_f32 v171, v171, s34, v227
	v_pk_mul_f32 v[164:165], v[164:165], s[44:45]
	v_pk_mul_f32 v[166:167], v[166:167], s[44:45]
	v_pk_mul_f32 v[168:169], v[168:169], s[44:45]
	v_pk_mul_f32 v[170:171], v[170:171], s[44:45]
	v_exp_f32_e32 v164, v164
	v_exp_f32_e32 v165, v165
	v_exp_f32_e32 v166, v166
	v_exp_f32_e32 v167, v167
	v_exp_f32_e32 v168, v168
	v_exp_f32_e32 v169, v169
	v_exp_f32_e32 v170, v170
	v_exp_f32_e32 v171, v171
	v_pk_add_f32 v[164:165], v[164:165], 1.0 op_sel_hi:[1,0]
	v_pk_add_f32 v[166:167], v[166:167], 1.0 op_sel_hi:[1,0]
	v_pk_add_f32 v[168:169], v[168:169], 1.0 op_sel_hi:[1,0]
	v_pk_add_f32 v[170:171], v[170:171], 1.0 op_sel_hi:[1,0]
	v_rcp_f32_e32 v164, v164
	v_rcp_f32_e32 v165, v165
	v_rcp_f32_e32 v166, v166
	v_rcp_f32_e32 v167, v167
	v_rcp_f32_e32 v168, v168
	v_rcp_f32_e32 v169, v169
	v_rcp_f32_e32 v170, v170
	v_rcp_f32_e32 v171, v171
	v_pk_mul_f32 v[164:165], v[24:25], v[164:165]
	v_pk_mul_f32 v[166:167], v[26:27], v[166:167]
	v_pk_mul_f32 v[168:169], v[20:21], v[168:169]
	v_pk_mul_f32 v[170:171], v[22:23], v[170:171]
	v_cvt_pk_bf16_f32 v174, v164, v165
	v_cvt_pk_bf16_f32 v175, v166, v167
	v_cvt_pk_bf16_f32 v176, v168, v169
	v_cvt_pk_bf16_f32 v177, v170, v171
	global_store_dwordx4 v1, v[174:177], s[22:23] offset:-3840
	s_mov_b64 s[40:41], 0
	s_branch .LBB0_206

.LBB0_242:
	s_add_u32 s23, s0, 0xfffc0080
	s_addc_u32 s24, s1, -1
	s_add_i32 s25, 0, 0x10000
	v_add_u32_e32 v2, s25, v187
	ds_read_b128 v[132:135], v2
	ds_read_b128 v[136:139], v2 offset:1024
	ds_read_b128 v[140:143], v2 offset:2048
	ds_read_b128 v[144:147], v2 offset:3072
	s_cmp_eq_u32 s22, 12
	s_cselect_b32 s47, s57, s24
	s_cselect_b32 s46, s56, s23
	s_cselect_b32 s45, s59, s21
	s_cselect_b32 s44, s58, s20
	v_lshl_add_u64 v[208:209], s[0:1], 0, v[194:195]
	s_add_i32 m0, s67, 0xc000
	ds_read_b128 v[148:151], v240
	ds_read_b128 v[152:155], v240 offset:1024
	ds_read_b128 v[156:159], v240 offset:2048
	ds_read_b128 v[160:163], v240 offset:3072
	ds_read_b128 v[164:167], v240 offset:4096
	ds_read_b128 v[168:171], v240 offset:5120
	ds_read_b128 v[172:175], v240 offset:6144
	ds_read_b128 v[204:207], v240 offset:7168
	global_load_lds_dwordx4 v[208:209], off
	v_lshl_add_u64 v[208:209], s[0:1], 0, v[202:203]
	s_add_i32 m0, s67, 0xe000
	s_nop 0
	global_load_lds_dwordx4 v[208:209], off
	s_waitcnt lgkmcnt(8)
	s_barrier
	s_waitcnt lgkmcnt(0)
	s_waitcnt lgkmcnt(0)
	v_mfma_f32_16x16x32_bf16 v[128:131], v[132:135], v[148:151], v[128:131]
	v_mfma_f32_16x16x32_bf16 v[124:127], v[140:143], v[148:151], v[124:127]
	v_mfma_f32_16x16x32_bf16 v[120:123], v[132:135], v[156:159], v[120:123]
	v_mfma_f32_16x16x32_bf16 v[116:119], v[140:143], v[156:159], v[116:119]
	v_mfma_f32_16x16x32_bf16 v[112:115], v[132:135], v[164:167], v[112:115]
	v_mfma_f32_16x16x32_bf16 v[108:111], v[140:143], v[164:167], v[108:111]
	v_mfma_f32_16x16x32_bf16 v[104:107], v[132:135], v[172:175], v[104:107]
	v_mfma_f32_16x16x32_bf16 v[100:103], v[140:143], v[172:175], v[100:103]
	v_mfma_f32_16x16x32_bf16 v[128:131], v[136:139], v[152:155], v[128:131]
	v_mfma_f32_16x16x32_bf16 v[124:127], v[144:147], v[152:155], v[124:127]
	v_mfma_f32_16x16x32_bf16 v[120:123], v[136:139], v[160:163], v[120:123]
	v_mfma_f32_16x16x32_bf16 v[116:119], v[144:147], v[160:163], v[116:119]
	v_mfma_f32_16x16x32_bf16 v[112:115], v[136:139], v[168:171], v[112:115]
	v_mfma_f32_16x16x32_bf16 v[108:111], v[144:147], v[168:171], v[108:111]
	v_mfma_f32_16x16x32_bf16 v[104:107], v[136:139], v[204:207], v[104:107]
	v_mfma_f32_16x16x32_bf16 v[100:103], v[144:147], v[204:207], v[100:103]
	s_barrier
	s_add_i32 s23, 0, 0x14000
	s_add_i32 s24, s25, s61
	v_add_u32_e32 v2, s23, v187
	v_lshl_add_u64 v[222:223], s[44:45], 0, v[176:177]
	s_mov_b32 m0, s24
	ds_read_b128 v[208:211], v2
	ds_read_b128 v[212:215], v2 offset:1024
	ds_read_b128 v[242:245], v2 offset:2048
	ds_read_b128 v[246:249], v2 offset:3072
	global_load_lds_dwordx4 v[222:223], off
	v_lshl_add_u64 v[250:251], s[44:45], 0, v[180:181]
	s_add_i32 m0, s24, 0x2000
	s_nop 0
	global_load_lds_dwordx4 v[250:251], off
	s_barrier
	s_waitcnt lgkmcnt(0)
	s_waitcnt lgkmcnt(0)
	v_mfma_f32_16x16x32_bf16 v[64:67], v[208:211], v[148:151], v[64:67]
	v_mfma_f32_16x16x32_bf16 v[60:63], v[242:245], v[148:151], v[60:63]
	v_mfma_f32_16x16x32_bf16 v[56:59], v[208:211], v[156:159], v[56:59]
	v_mfma_f32_16x16x32_bf16 v[52:55], v[242:245], v[156:159], v[52:55]
	v_mfma_f32_16x16x32_bf16 v[48:51], v[208:211], v[164:167], v[48:51]
	v_mfma_f32_16x16x32_bf16 v[44:47], v[242:245], v[164:167], v[44:47]
	v_mfma_f32_16x16x32_bf16 v[40:43], v[208:211], v[172:175], v[40:43]
	v_mfma_f32_16x16x32_bf16 v[36:39], v[242:245], v[172:175], v[36:39]
	v_mfma_f32_16x16x32_bf16 v[64:67], v[212:215], v[152:155], v[64:67]
	v_mfma_f32_16x16x32_bf16 v[60:63], v[246:249], v[152:155], v[60:63]
	v_mfma_f32_16x16x32_bf16 v[56:59], v[212:215], v[160:163], v[56:59]
	v_mfma_f32_16x16x32_bf16 v[52:55], v[246:249], v[160:163], v[52:55]
	v_mfma_f32_16x16x32_bf16 v[48:51], v[212:215], v[168:171], v[48:51]
	v_mfma_f32_16x16x32_bf16 v[44:47], v[246:249], v[168:171], v[44:47]
	v_mfma_f32_16x16x32_bf16 v[40:43], v[212:215], v[204:207], v[40:43]
	v_mfma_f32_16x16x32_bf16 v[36:39], v[246:249], v[204:207], v[36:39]
	s_mov_b32 m0, s67
	v_lshl_add_u64 v[216:217], s[46:47], 0, v[0:1]
	s_barrier
	ds_read_b128 v[148:151], v240 offset:16384
	ds_read_b128 v[152:155], v240 offset:17408
	ds_read_b128 v[156:159], v240 offset:18432
	ds_read_b128 v[160:163], v240 offset:19456
	ds_read_b128 v[164:167], v240 offset:20480
	ds_read_b128 v[168:171], v240 offset:21504
	ds_read_b128 v[172:175], v240 offset:22528
	ds_read_b128 v[204:207], v240 offset:23552
	global_load_lds_dwordx4 v[216:217], off
	v_lshl_add_u64 v[236:237], s[46:47], 0, v[178:179]
	s_mov_b32 m0, s74
	s_nop 0
	global_load_lds_dwordx4 v[236:237], off
	s_barrier
	s_waitcnt lgkmcnt(0)
	s_waitcnt lgkmcnt(0)
	v_mfma_f32_16x16x32_bf16 v[96:99], v[132:135], v[148:151], v[96:99]
	v_mfma_f32_16x16x32_bf16 v[92:95], v[140:143], v[148:151], v[92:95]
	v_mfma_f32_16x16x32_bf16 v[88:91], v[132:135], v[156:159], v[88:91]
	v_mfma_f32_16x16x32_bf16 v[84:87], v[140:143], v[156:159], v[84:87]
	v_mfma_f32_16x16x32_bf16 v[80:83], v[132:135], v[164:167], v[80:83]
	v_mfma_f32_16x16x32_bf16 v[76:79], v[140:143], v[164:167], v[76:79]
	v_mfma_f32_16x16x32_bf16 v[72:75], v[132:135], v[172:175], v[72:75]
	v_mfma_f32_16x16x32_bf16 v[68:71], v[140:143], v[172:175], v[68:71]
	v_mfma_f32_16x16x32_bf16 v[96:99], v[136:139], v[152:155], v[96:99]
	v_mfma_f32_16x16x32_bf16 v[92:95], v[144:147], v[152:155], v[92:95]
	v_mfma_f32_16x16x32_bf16 v[88:91], v[136:139], v[160:163], v[88:91]
	v_mfma_f32_16x16x32_bf16 v[84:87], v[144:147], v[160:163], v[84:87]
	v_mfma_f32_16x16x32_bf16 v[80:83], v[136:139], v[168:171], v[80:83]
	v_mfma_f32_16x16x32_bf16 v[76:79], v[144:147], v[168:171], v[76:79]
	v_mfma_f32_16x16x32_bf16 v[72:75], v[136:139], v[204:207], v[72:75]
	v_mfma_f32_16x16x32_bf16 v[68:71], v[144:147], v[204:207], v[68:71]
	s_barrier
	s_add_u32 s24, s44, 0x40000
	s_addc_u32 s25, s45, 0
	s_add_i32 s23, s23, s61
	v_lshl_add_u64 v[132:133], s[24:25], 0, v[176:177]
	s_mov_b32 m0, s23
	s_nop 0
	global_load_lds_dwordx4 v[132:133], off
	v_lshl_add_u64 v[132:133], s[24:25], 0, v[180:181]
	s_add_i32 m0, s23, 0x2000
	s_nop 0
	global_load_lds_dwordx4 v[132:133], off
	s_waitcnt vmcnt(6)
	s_barrier
	v_mfma_f32_16x16x32_bf16 v[32:35], v[208:211], v[148:151], v[32:35]
	v_mfma_f32_16x16x32_bf16 v[28:31], v[242:245], v[148:151], v[28:31]
	v_mfma_f32_16x16x32_bf16 v[24:27], v[208:211], v[156:159], v[24:27]
	v_mfma_f32_16x16x32_bf16 v[20:23], v[242:245], v[156:159], v[20:23]
	v_mfma_f32_16x16x32_bf16 v[16:19], v[208:211], v[164:167], v[16:19]
	v_mfma_f32_16x16x32_bf16 v[12:15], v[242:245], v[164:167], v[12:15]
	v_mfma_f32_16x16x32_bf16 v[8:11], v[208:211], v[172:175], v[8:11]
	v_mfma_f32_16x16x32_bf16 v[4:7], v[242:245], v[172:175], v[4:7]
	v_mfma_f32_16x16x32_bf16 v[32:35], v[212:215], v[152:155], v[32:35]
	v_mfma_f32_16x16x32_bf16 v[28:31], v[246:249], v[152:155], v[28:31]
	v_mfma_f32_16x16x32_bf16 v[24:27], v[212:215], v[160:163], v[24:27]
	v_mfma_f32_16x16x32_bf16 v[20:23], v[246:249], v[160:163], v[20:23]
	v_mfma_f32_16x16x32_bf16 v[16:19], v[212:215], v[168:171], v[16:19]
	v_mfma_f32_16x16x32_bf16 v[12:15], v[246:249], v[168:171], v[12:15]
	v_mfma_f32_16x16x32_bf16 v[8:11], v[212:215], v[204:207], v[8:11]
	v_mfma_f32_16x16x32_bf16 v[4:7], v[246:249], v[204:207], v[4:7]
	s_add_i32 s23, 0, 0x18000
	v_add_u32_e32 v2, s23, v187
	s_barrier
	ds_read_b128 v[132:135], v2
	ds_read_b128 v[136:139], v2 offset:1024
	ds_read_b128 v[140:143], v2 offset:2048
	ds_read_b128 v[144:147], v2 offset:3072
	s_add_u32 s24, s46, 0x40000
	s_addc_u32 s25, s47, 0
	s_mov_b32 m0, s75
	v_lshl_add_u64 v[208:209], s[24:25], 0, v[0:1]
	ds_read_b128 v[148:151], v240 offset:32768
	ds_read_b128 v[152:155], v240 offset:33792
	ds_read_b128 v[156:159], v240 offset:34816
	ds_read_b128 v[160:163], v240 offset:35840
	ds_read_b128 v[164:167], v240 offset:36864
	ds_read_b128 v[168:171], v240 offset:37888
	ds_read_b128 v[172:175], v240 offset:38912
	ds_read_b128 v[204:207], v240 offset:39936
	global_load_lds_dwordx4 v[208:209], off
	v_lshl_add_u64 v[208:209], s[24:25], 0, v[178:179]
	s_mov_b32 m0, s82
	s_nop 0
	global_load_lds_dwordx4 v[208:209], off
	s_waitcnt lgkmcnt(8)
	s_barrier
	s_waitcnt lgkmcnt(0)
	s_waitcnt lgkmcnt(0)
	v_mfma_f32_16x16x32_bf16 v[128:131], v[132:135], v[148:151], v[128:131]
	v_mfma_f32_16x16x32_bf16 v[124:127], v[140:143], v[148:151], v[124:127]
	v_mfma_f32_16x16x32_bf16 v[120:123], v[132:135], v[156:159], v[120:123]
	v_mfma_f32_16x16x32_bf16 v[116:119], v[140:143], v[156:159], v[116:119]
	v_mfma_f32_16x16x32_bf16 v[112:115], v[132:135], v[164:167], v[112:115]
	v_mfma_f32_16x16x32_bf16 v[108:111], v[140:143], v[164:167], v[108:111]
	v_mfma_f32_16x16x32_bf16 v[104:107], v[132:135], v[172:175], v[104:107]
	v_mfma_f32_16x16x32_bf16 v[100:103], v[140:143], v[172:175], v[100:103]
	v_mfma_f32_16x16x32_bf16 v[128:131], v[136:139], v[152:155], v[128:131]
	v_mfma_f32_16x16x32_bf16 v[124:127], v[144:147], v[152:155], v[124:127]
	v_mfma_f32_16x16x32_bf16 v[120:123], v[136:139], v[160:163], v[120:123]
	v_mfma_f32_16x16x32_bf16 v[116:119], v[144:147], v[160:163], v[116:119]
	v_mfma_f32_16x16x32_bf16 v[112:115], v[136:139], v[168:171], v[112:115]
	v_mfma_f32_16x16x32_bf16 v[108:111], v[144:147], v[168:171], v[108:111]
	v_mfma_f32_16x16x32_bf16 v[104:107], v[136:139], v[204:207], v[104:107]
	v_mfma_f32_16x16x32_bf16 v[100:103], v[144:147], v[204:207], v[100:103]
	s_barrier
	s_add_i32 s26, 0, 0x1c000
	s_add_i32 s23, s23, s61
	v_add_u32_e32 v2, s26, v187
	v_lshl_add_u64 v[222:223], v[222:223], 0, s[76:77]
	s_mov_b32 m0, s23
	ds_read_b128 v[208:211], v2
	ds_read_b128 v[212:215], v2 offset:1024
	ds_read_b128 v[242:245], v2 offset:2048
	ds_read_b128 v[246:249], v2 offset:3072
	global_load_lds_dwordx4 v[222:223], off
	v_lshl_add_u64 v[222:223], v[250:251], 0, s[76:77]
	s_add_i32 m0, s23, 0x2000
	s_nop 0
	global_load_lds_dwordx4 v[222:223], off
	s_barrier
	s_waitcnt lgkmcnt(0)
	s_waitcnt lgkmcnt(0)
	v_mfma_f32_16x16x32_bf16 v[64:67], v[208:211], v[148:151], v[64:67]
	v_mfma_f32_16x16x32_bf16 v[60:63], v[242:245], v[148:151], v[60:63]
	v_mfma_f32_16x16x32_bf16 v[56:59], v[208:211], v[156:159], v[56:59]
	v_mfma_f32_16x16x32_bf16 v[52:55], v[242:245], v[156:159], v[52:55]
	v_mfma_f32_16x16x32_bf16 v[48:51], v[208:211], v[164:167], v[48:51]
	v_mfma_f32_16x16x32_bf16 v[44:47], v[242:245], v[164:167], v[44:47]
	v_mfma_f32_16x16x32_bf16 v[40:43], v[208:211], v[172:175], v[40:43]
	v_mfma_f32_16x16x32_bf16 v[36:39], v[242:245], v[172:175], v[36:39]
	v_mfma_f32_16x16x32_bf16 v[64:67], v[212:215], v[152:155], v[64:67]
	v_mfma_f32_16x16x32_bf16 v[60:63], v[246:249], v[152:155], v[60:63]
	v_mfma_f32_16x16x32_bf16 v[56:59], v[212:215], v[160:163], v[56:59]
	v_mfma_f32_16x16x32_bf16 v[52:55], v[246:249], v[160:163], v[52:55]
	v_mfma_f32_16x16x32_bf16 v[48:51], v[212:215], v[168:171], v[48:51]
	v_mfma_f32_16x16x32_bf16 v[44:47], v[246:249], v[168:171], v[44:47]
	v_mfma_f32_16x16x32_bf16 v[40:43], v[212:215], v[204:207], v[40:43]
	v_mfma_f32_16x16x32_bf16 v[36:39], v[246:249], v[204:207], v[36:39]
	s_mov_b32 m0, s48
	v_lshl_add_u64 v[216:217], v[216:217], 0, s[76:77]
	s_barrier
	ds_read_b128 v[148:151], v240 offset:49152
	ds_read_b128 v[152:155], v240 offset:50176
	ds_read_b128 v[156:159], v240 offset:51200
	ds_read_b128 v[160:163], v240 offset:52224
	ds_read_b128 v[164:167], v240 offset:53248
	ds_read_b128 v[168:171], v240 offset:54272
	ds_read_b128 v[172:175], v240 offset:55296
	ds_read_b128 v[204:207], v240 offset:56320
	global_load_lds_dwordx4 v[216:217], off
	v_lshl_add_u64 v[216:217], v[236:237], 0, s[76:77]
	s_mov_b32 m0, s50
	s_nop 0
	global_load_lds_dwordx4 v[216:217], off
	s_barrier
	s_waitcnt lgkmcnt(0)
	s_waitcnt lgkmcnt(0)
	v_mfma_f32_16x16x32_bf16 v[96:99], v[132:135], v[148:151], v[96:99]
	v_mfma_f32_16x16x32_bf16 v[92:95], v[140:143], v[148:151], v[92:95]
	v_mfma_f32_16x16x32_bf16 v[88:91], v[132:135], v[156:159], v[88:91]
	v_mfma_f32_16x16x32_bf16 v[84:87], v[140:143], v[156:159], v[84:87]
	v_mfma_f32_16x16x32_bf16 v[80:83], v[132:135], v[164:167], v[80:83]
	v_mfma_f32_16x16x32_bf16 v[76:79], v[140:143], v[164:167], v[76:79]
	v_mfma_f32_16x16x32_bf16 v[72:75], v[132:135], v[172:175], v[72:75]
	v_mfma_f32_16x16x32_bf16 v[68:71], v[140:143], v[172:175], v[68:71]
	v_mfma_f32_16x16x32_bf16 v[96:99], v[136:139], v[152:155], v[96:99]
	v_mfma_f32_16x16x32_bf16 v[92:95], v[144:147], v[152:155], v[92:95]
	v_mfma_f32_16x16x32_bf16 v[88:91], v[136:139], v[160:163], v[88:91]
	v_mfma_f32_16x16x32_bf16 v[84:87], v[144:147], v[160:163], v[84:87]
	v_mfma_f32_16x16x32_bf16 v[80:83], v[136:139], v[168:171], v[80:83]
	v_mfma_f32_16x16x32_bf16 v[76:79], v[144:147], v[168:171], v[76:79]
	v_mfma_f32_16x16x32_bf16 v[72:75], v[136:139], v[204:207], v[72:75]
	v_mfma_f32_16x16x32_bf16 v[68:71], v[144:147], v[204:207], v[68:71]
	s_barrier
	s_add_u32 s24, s44, 0x40080
	s_addc_u32 s25, s45, 0
	s_add_i32 s23, s26, s61
	v_lshl_add_u64 v[132:133], s[24:25], 0, v[176:177]
	s_mov_b32 m0, s23
	s_nop 0
	global_load_lds_dwordx4 v[132:133], off
	v_lshl_add_u64 v[132:133], s[24:25], 0, v[180:181]
	s_add_i32 m0, s23, 0x2000
	s_nop 0
	global_load_lds_dwordx4 v[132:133], off
	s_waitcnt vmcnt(6)
	s_barrier
	v_mfma_f32_16x16x32_bf16 v[32:35], v[208:211], v[148:151], v[32:35]
	v_mfma_f32_16x16x32_bf16 v[28:31], v[242:245], v[148:151], v[28:31]
	v_mfma_f32_16x16x32_bf16 v[24:27], v[208:211], v[156:159], v[24:27]
	v_mfma_f32_16x16x32_bf16 v[20:23], v[242:245], v[156:159], v[20:23]
	v_mfma_f32_16x16x32_bf16 v[16:19], v[208:211], v[164:167], v[16:19]
	v_mfma_f32_16x16x32_bf16 v[12:15], v[242:245], v[164:167], v[12:15]
	v_mfma_f32_16x16x32_bf16 v[8:11], v[208:211], v[172:175], v[8:11]
	v_mfma_f32_16x16x32_bf16 v[4:7], v[242:245], v[172:175], v[4:7]
	v_mfma_f32_16x16x32_bf16 v[32:35], v[212:215], v[152:155], v[32:35]
	v_mfma_f32_16x16x32_bf16 v[28:31], v[246:249], v[152:155], v[28:31]
	v_mfma_f32_16x16x32_bf16 v[24:27], v[212:215], v[160:163], v[24:27]
	v_mfma_f32_16x16x32_bf16 v[20:23], v[246:249], v[160:163], v[20:23]
	v_mfma_f32_16x16x32_bf16 v[16:19], v[212:215], v[168:171], v[16:19]
	v_mfma_f32_16x16x32_bf16 v[12:15], v[246:249], v[168:171], v[12:15]
	v_mfma_f32_16x16x32_bf16 v[8:11], v[212:215], v[204:207], v[8:11]
	v_mfma_f32_16x16x32_bf16 v[4:7], v[246:249], v[204:207], v[4:7]
	s_add_i32 s22, s22, 2
	s_add_u32 s0, s0, 0x100
	s_addc_u32 s1, s1, 0
	s_add_u32 s20, s20, 0x100
	s_addc_u32 s21, s21, 0
	s_cmp_gt_u32 s22, 13
	s_barrier
	s_cbranch_scc0 .LBB0_242
	s_add_i32 s0, s66, -8
	s_cmp_lt_u32 s0, 12
	s_mov_b64 s[0:1], -1
	s_cbranch_scc1 .LBB0_266
	s_cmp_gt_i32 s66, 33
	s_cselect_b64 s[64:65], -1, 0
	s_lshl_b32 s0, s66, 8
	s_lshl_b32 s53, s60, 8
	s_add_i32 s1, s0, 0xffffee00
	s_cmp_lt_i32 s66, 26
	v_cndmask_b32_e64 v2, 0, 1, s[80:81]
	s_cselect_b32 s62, s0, s1
	s_mov_b64 s[0:1], -1
	s_and_b64 vcc, exec, s[64:65]
	v_cmp_ne_u32_e64 s[44:45], 1, v2
	s_cbranch_vccz .LBB0_248
	s_and_b64 vcc, exec, s[44:45]
	s_cbranch_vccnz .LBB0_247
	v_add_u32_e32 v132, s53, v185
	v_ashrrev_i32_e32 v133, 31, v132
	v_lshlrev_b64 v[140:141], 7, v[132:133]
	global_load_dwordx4 v[132:135], v[188:189], off offset:16
	global_load_dwordx4 v[136:139], v[188:189], off
	s_mov_b32 s3, 0xbfb8aa3b
	s_mov_b32 s2, 0x800000
	s_mov_b32 s5, 0x3f317217
	s_mov_b32 s6, 0x7f800000
	s_waitcnt vmcnt(0)
	v_add_f32_e32 v147, v126, v134
	v_add_f32_e32 v2, v128, v136
	v_max_f32_e32 v142, 0, v2
	v_mul_f32_e64 v2, |v2|, s3
	v_exp_f32_e32 v2, v2
	v_add_f32_e32 v136, v124, v132
	v_add_f32_e32 v149, v127, v135
	v_add_f32_e32 v2, 1.0, v2
	v_cmp_gt_f32_e32 vcc, s2, v2
	s_nop 1
	v_cndmask_b32_e64 v132, 0, 32, vcc
	v_ldexp_f32 v2, v2, v132
	v_log_f32_e32 v2, v2
	s_nop 0
	v_mul_f32_e32 v132, 0x3f317217, v2
	v_fma_f32 v132, v2, s5, -v132
	v_fmac_f32_e32 v132, 0x3377d1cf, v2
	v_fmac_f32_e32 v132, 0x3f317217, v2
	v_cmp_lt_f32_e64 s[0:1], |v2|, s6
	s_nop 1
	v_cndmask_b32_e64 v2, v2, v132, s[0:1]
	v_cndmask_b32_e32 v132, 0, v228, vcc
	v_sub_f32_e32 v144, v2, v132
	v_mul_f32_e64 v2, |v136|, s3
	v_exp_f32_e32 v2, v2
	v_max_f32_e32 v132, 0, v136
	v_add_f32_e32 v2, 1.0, v2
	v_cmp_gt_f32_e32 vcc, s2, v2
	s_nop 1
	v_cndmask_b32_e64 v136, 0, 32, vcc
	v_ldexp_f32 v2, v2, v136
	v_log_f32_e32 v2, v2
	s_nop 0
	v_mul_f32_e32 v136, 0x3f317217, v2
	v_fma_f32 v136, v2, s5, -v136
	v_fmac_f32_e32 v136, 0x3377d1cf, v2
	v_fmac_f32_e32 v136, 0x3f317217, v2
	v_cmp_lt_f32_e64 s[0:1], |v2|, s6
	s_nop 1
	v_cndmask_b32_e64 v2, v2, v136, s[0:1]
	v_cndmask_b32_e32 v136, 0, v228, vcc
	v_sub_f32_e32 v136, v2, v136
	v_add_f32_e32 v2, v129, v137
	v_max_f32_e32 v143, 0, v2
	v_mul_f32_e64 v2, |v2|, s3
	v_exp_f32_e32 v2, v2
	v_add_f32_e32 v137, v125, v133
	v_add_f32_e32 v2, 1.0, v2
	v_cmp_gt_f32_e32 vcc, s2, v2
	s_nop 1
	v_cndmask_b32_e64 v133, 0, 32, vcc
	v_ldexp_f32 v2, v2, v133
	v_log_f32_e32 v2, v2
	s_nop 0
	v_mul_f32_e32 v133, 0x3f317217, v2
	v_fma_f32 v133, v2, s5, -v133
	v_fmac_f32_e32 v133, 0x3377d1cf, v2
	v_fmac_f32_e32 v133, 0x3f317217, v2
	v_cmp_lt_f32_e64 s[0:1], |v2|, s6
	s_nop 1
	v_cndmask_b32_e64 v2, v2, v133, s[0:1]
	v_cndmask_b32_e32 v133, 0, v228, vcc
	v_sub_f32_e32 v145, v2, v133
	v_mul_f32_e64 v2, |v137|, s3
	v_exp_f32_e32 v2, v2
	v_max_f32_e32 v133, 0, v137
	v_pk_add_f32 v[142:143], v[142:143], v[144:145]
	v_add_f32_e32 v2, 1.0, v2
	v_cmp_gt_f32_e32 vcc, s2, v2
	s_nop 1
	v_cndmask_b32_e64 v137, 0, 32, vcc
	v_ldexp_f32 v2, v2, v137
	v_log_f32_e32 v2, v2
	s_nop 0
	v_mul_f32_e32 v137, 0x3f317217, v2
	v_fma_f32 v137, v2, s5, -v137
	v_fmac_f32_e32 v137, 0x3377d1cf, v2
	v_fmac_f32_e32 v137, 0x3f317217, v2
	v_cmp_lt_f32_e64 s[0:1], |v2|, s6
	s_nop 1
	v_cndmask_b32_e64 v2, v2, v137, s[0:1]
	v_cndmask_b32_e32 v137, 0, v228, vcc
	v_sub_f32_e32 v137, v2, v137
	v_add_f32_e32 v2, v130, v138
	v_max_f32_e32 v138, 0, v2
	v_mul_f32_e64 v2, |v2|, s3
	v_exp_f32_e32 v2, v2
	v_pk_add_f32 v[132:133], v[132:133], v[136:137]
	v_lshl_add_u64 v[136:137], v[190:191], 0, v[140:141]
	v_add_f32_e32 v2, 1.0, v2
	v_cmp_gt_f32_e32 vcc, s2, v2
	s_nop 1
	v_cndmask_b32_e64 v134, 0, 32, vcc
	v_ldexp_f32 v2, v2, v134
	v_log_f32_e32 v2, v2
	s_nop 0
	v_mul_f32_e32 v134, 0x3f317217, v2
	v_fma_f32 v134, v2, s5, -v134
	v_fmac_f32_e32 v134, 0x3377d1cf, v2
	v_fmac_f32_e32 v134, 0x3f317217, v2
	v_cmp_lt_f32_e64 s[0:1], |v2|, s6
	s_nop 1
	v_cndmask_b32_e64 v2, v2, v134, s[0:1]
	v_cndmask_b32_e32 v134, 0, v228, vcc
	v_sub_f32_e32 v146, v2, v134
	v_mul_f32_e64 v2, |v147|, s3
	v_exp_f32_e32 v2, v2
	v_max_f32_e32 v134, 0, v147
	v_add_f32_e32 v2, 1.0, v2
	v_cmp_gt_f32_e32 vcc, s2, v2
	s_nop 1
	v_cndmask_b32_e64 v147, 0, 32, vcc
	v_ldexp_f32 v2, v2, v147
	v_log_f32_e32 v2, v2
	s_nop 0
	v_mul_f32_e32 v147, 0x3f317217, v2
	v_fma_f32 v147, v2, s5, -v147
	v_fmac_f32_e32 v147, 0x3377d1cf, v2
	v_fmac_f32_e32 v147, 0x3f317217, v2
	v_cmp_lt_f32_e64 s[0:1], |v2|, s6
	s_nop 1
	v_cndmask_b32_e64 v2, v2, v147, s[0:1]
	v_cndmask_b32_e32 v147, 0, v228, vcc
	v_sub_f32_e32 v148, v2, v147
	v_add_f32_e32 v2, v131, v139
	v_max_f32_e32 v139, 0, v2
	v_mul_f32_e64 v2, |v2|, s3
	v_exp_f32_e32 v2, v2
	s_nop 0
	v_add_f32_e32 v2, 1.0, v2
	v_cmp_gt_f32_e32 vcc, s2, v2
	s_nop 1
	v_cndmask_b32_e64 v135, 0, 32, vcc
	v_ldexp_f32 v2, v2, v135
	v_log_f32_e32 v2, v2
	s_nop 0
	v_mul_f32_e32 v135, 0x3f317217, v2
	v_fma_f32 v135, v2, s5, -v135
	v_fmac_f32_e32 v135, 0x3377d1cf, v2
	v_fmac_f32_e32 v135, 0x3f317217, v2
	v_cmp_lt_f32_e64 s[0:1], |v2|, s6
	s_nop 1
	v_cndmask_b32_e64 v2, v2, v135, s[0:1]
	v_cndmask_b32_e32 v135, 0, v228, vcc
	v_sub_f32_e32 v147, v2, v135
	v_mul_f32_e64 v2, |v149|, s3
	v_exp_f32_e32 v2, v2
	v_pk_add_f32 v[144:145], v[138:139], v[146:147]
	v_max_f32_e32 v135, 0, v149
	v_add_f32_e32 v2, 1.0, v2
	v_cmp_gt_f32_e32 vcc, s2, v2
	s_nop 1
	v_cndmask_b32_e64 v138, 0, 32, vcc
	v_ldexp_f32 v2, v2, v138
	v_log_f32_e32 v2, v2
	s_nop 0
	v_mul_f32_e32 v138, 0x3f317217, v2
	v_fma_f32 v138, v2, s5, -v138
	v_fmac_f32_e32 v138, 0x3377d1cf, v2
	v_fmac_f32_e32 v138, 0x3f317217, v2
	v_cmp_lt_f32_e64 s[0:1], |v2|, s6
	s_nop 1
	v_cndmask_b32_e64 v2, v2, v138, s[0:1]
	v_cndmask_b32_e32 v138, 0, v228, vcc
	v_sub_f32_e32 v149, v2, v138
	v_pk_add_f32 v[134:135], v[134:135], v[148:149]
	global_store_dwordx4 v[136:137], v[142:145], off
	global_store_dwordx4 v[136:137], v[132:135], off offset:16

.LBB0_427:
	s_add_u32 s23, s0, 0xfffc0080
	s_addc_u32 s24, s1, -1
	s_add_i32 s25, 0, 0x10000
	v_add_u32_e32 v2, s25, v187
	ds_read_b128 v[132:135], v2
	ds_read_b128 v[136:139], v2 offset:1024
	ds_read_b128 v[140:143], v2 offset:2048
	ds_read_b128 v[144:147], v2 offset:3072
	s_cmp_eq_u32 s22, 12
	s_cselect_b32 s47, s57, s24
	s_cselect_b32 s46, s56, s23
	s_cselect_b32 s45, s59, s21
	s_cselect_b32 s44, s58, s20
	v_lshl_add_u64 v[208:209], s[0:1], 0, v[194:195]
	s_add_i32 m0, s74, 0xc000
	ds_read_b128 v[148:151], v240
	ds_read_b128 v[152:155], v240 offset:1024
	ds_read_b128 v[156:159], v240 offset:2048
	ds_read_b128 v[160:163], v240 offset:3072
	ds_read_b128 v[164:167], v240 offset:4096
	ds_read_b128 v[168:171], v240 offset:5120
	ds_read_b128 v[172:175], v240 offset:6144
	ds_read_b128 v[204:207], v240 offset:7168
	global_load_lds_dwordx4 v[208:209], off
	v_lshl_add_u64 v[208:209], s[0:1], 0, v[202:203]
	s_add_i32 m0, s74, 0xe000
	s_nop 0
	global_load_lds_dwordx4 v[208:209], off
	s_waitcnt lgkmcnt(8)
	s_barrier
	s_waitcnt lgkmcnt(0)
	s_waitcnt lgkmcnt(0)
	v_mfma_f32_16x16x32_bf16 v[128:131], v[132:135], v[148:151], v[128:131]
	v_mfma_f32_16x16x32_bf16 v[124:127], v[140:143], v[148:151], v[124:127]
	v_mfma_f32_16x16x32_bf16 v[120:123], v[132:135], v[156:159], v[120:123]
	v_mfma_f32_16x16x32_bf16 v[116:119], v[140:143], v[156:159], v[116:119]
	v_mfma_f32_16x16x32_bf16 v[112:115], v[132:135], v[164:167], v[112:115]
	v_mfma_f32_16x16x32_bf16 v[108:111], v[140:143], v[164:167], v[108:111]
	v_mfma_f32_16x16x32_bf16 v[104:107], v[132:135], v[172:175], v[104:107]
	v_mfma_f32_16x16x32_bf16 v[100:103], v[140:143], v[172:175], v[100:103]
	v_mfma_f32_16x16x32_bf16 v[128:131], v[136:139], v[152:155], v[128:131]
	v_mfma_f32_16x16x32_bf16 v[124:127], v[144:147], v[152:155], v[124:127]
	v_mfma_f32_16x16x32_bf16 v[120:123], v[136:139], v[160:163], v[120:123]
	v_mfma_f32_16x16x32_bf16 v[116:119], v[144:147], v[160:163], v[116:119]
	v_mfma_f32_16x16x32_bf16 v[112:115], v[136:139], v[168:171], v[112:115]
	v_mfma_f32_16x16x32_bf16 v[108:111], v[144:147], v[168:171], v[108:111]
	v_mfma_f32_16x16x32_bf16 v[104:107], v[136:139], v[204:207], v[104:107]
	v_mfma_f32_16x16x32_bf16 v[100:103], v[144:147], v[204:207], v[100:103]
	s_barrier
	s_add_i32 s23, 0, 0x14000
	s_add_i32 s24, s25, s67
	v_add_u32_e32 v2, s23, v187
	v_lshl_add_u64 v[250:251], s[44:45], 0, v[176:177]
	s_mov_b32 m0, s24
	ds_read_b128 v[208:211], v2
	ds_read_b128 v[212:215], v2 offset:1024
	ds_read_b128 v[242:245], v2 offset:2048
	ds_read_b128 v[246:249], v2 offset:3072
	global_load_lds_dwordx4 v[250:251], off
	v_lshl_add_u64 v[222:223], s[44:45], 0, v[180:181]
	s_add_i32 m0, s24, 0x2000
	s_nop 0
	global_load_lds_dwordx4 v[222:223], off
	s_barrier
	s_waitcnt lgkmcnt(0)
	s_waitcnt lgkmcnt(0)
	v_mfma_f32_16x16x32_bf16 v[64:67], v[208:211], v[148:151], v[64:67]
	v_mfma_f32_16x16x32_bf16 v[60:63], v[242:245], v[148:151], v[60:63]
	v_mfma_f32_16x16x32_bf16 v[56:59], v[208:211], v[156:159], v[56:59]
	v_mfma_f32_16x16x32_bf16 v[52:55], v[242:245], v[156:159], v[52:55]
	v_mfma_f32_16x16x32_bf16 v[48:51], v[208:211], v[164:167], v[48:51]
	v_mfma_f32_16x16x32_bf16 v[44:47], v[242:245], v[164:167], v[44:47]
	v_mfma_f32_16x16x32_bf16 v[40:43], v[208:211], v[172:175], v[40:43]
	v_mfma_f32_16x16x32_bf16 v[36:39], v[242:245], v[172:175], v[36:39]
	v_mfma_f32_16x16x32_bf16 v[64:67], v[212:215], v[152:155], v[64:67]
	v_mfma_f32_16x16x32_bf16 v[60:63], v[246:249], v[152:155], v[60:63]
	v_mfma_f32_16x16x32_bf16 v[56:59], v[212:215], v[160:163], v[56:59]
	v_mfma_f32_16x16x32_bf16 v[52:55], v[246:249], v[160:163], v[52:55]
	v_mfma_f32_16x16x32_bf16 v[48:51], v[212:215], v[168:171], v[48:51]
	v_mfma_f32_16x16x32_bf16 v[44:47], v[246:249], v[168:171], v[44:47]
	v_mfma_f32_16x16x32_bf16 v[40:43], v[212:215], v[204:207], v[40:43]
	v_mfma_f32_16x16x32_bf16 v[36:39], v[246:249], v[204:207], v[36:39]
	s_mov_b32 m0, s74
	v_lshl_add_u64 v[216:217], s[46:47], 0, v[0:1]
	s_barrier
	ds_read_b128 v[148:151], v240 offset:16384
	ds_read_b128 v[152:155], v240 offset:17408
	ds_read_b128 v[156:159], v240 offset:18432
	ds_read_b128 v[160:163], v240 offset:19456
	ds_read_b128 v[164:167], v240 offset:20480
	ds_read_b128 v[168:171], v240 offset:21504
	ds_read_b128 v[172:175], v240 offset:22528
	ds_read_b128 v[204:207], v240 offset:23552
	global_load_lds_dwordx4 v[216:217], off
	v_lshl_add_u64 v[236:237], s[46:47], 0, v[178:179]
	s_mov_b32 m0, s75
	s_nop 0
	global_load_lds_dwordx4 v[236:237], off
	s_barrier
	s_waitcnt lgkmcnt(0)
	s_waitcnt lgkmcnt(0)
	v_mfma_f32_16x16x32_bf16 v[96:99], v[132:135], v[148:151], v[96:99]
	v_mfma_f32_16x16x32_bf16 v[92:95], v[140:143], v[148:151], v[92:95]
	v_mfma_f32_16x16x32_bf16 v[88:91], v[132:135], v[156:159], v[88:91]
	v_mfma_f32_16x16x32_bf16 v[84:87], v[140:143], v[156:159], v[84:87]
	v_mfma_f32_16x16x32_bf16 v[80:83], v[132:135], v[164:167], v[80:83]
	v_mfma_f32_16x16x32_bf16 v[76:79], v[140:143], v[164:167], v[76:79]
	v_mfma_f32_16x16x32_bf16 v[72:75], v[132:135], v[172:175], v[72:75]
	v_mfma_f32_16x16x32_bf16 v[68:71], v[140:143], v[172:175], v[68:71]
	v_mfma_f32_16x16x32_bf16 v[96:99], v[136:139], v[152:155], v[96:99]
	v_mfma_f32_16x16x32_bf16 v[92:95], v[144:147], v[152:155], v[92:95]
	v_mfma_f32_16x16x32_bf16 v[88:91], v[136:139], v[160:163], v[88:91]
	v_mfma_f32_16x16x32_bf16 v[84:87], v[144:147], v[160:163], v[84:87]
	v_mfma_f32_16x16x32_bf16 v[80:83], v[136:139], v[168:171], v[80:83]
	v_mfma_f32_16x16x32_bf16 v[76:79], v[144:147], v[168:171], v[76:79]
	v_mfma_f32_16x16x32_bf16 v[72:75], v[136:139], v[204:207], v[72:75]
	v_mfma_f32_16x16x32_bf16 v[68:71], v[144:147], v[204:207], v[68:71]
	s_barrier
	s_add_u32 s24, s44, 0x40000
	s_addc_u32 s25, s45, 0
	s_add_i32 s23, s23, s67
	v_lshl_add_u64 v[132:133], s[24:25], 0, v[176:177]
	s_mov_b32 m0, s23
	s_nop 0
	global_load_lds_dwordx4 v[132:133], off
	v_lshl_add_u64 v[132:133], s[24:25], 0, v[180:181]
	s_add_i32 m0, s23, 0x2000
	s_nop 0
	global_load_lds_dwordx4 v[132:133], off
	s_waitcnt vmcnt(6)
	s_barrier
	v_mfma_f32_16x16x32_bf16 v[32:35], v[208:211], v[148:151], v[32:35]
	v_mfma_f32_16x16x32_bf16 v[28:31], v[242:245], v[148:151], v[28:31]
	v_mfma_f32_16x16x32_bf16 v[24:27], v[208:211], v[156:159], v[24:27]
	v_mfma_f32_16x16x32_bf16 v[20:23], v[242:245], v[156:159], v[20:23]
	v_mfma_f32_16x16x32_bf16 v[16:19], v[208:211], v[164:167], v[16:19]
	v_mfma_f32_16x16x32_bf16 v[12:15], v[242:245], v[164:167], v[12:15]
	v_mfma_f32_16x16x32_bf16 v[8:11], v[208:211], v[172:175], v[8:11]
	v_mfma_f32_16x16x32_bf16 v[4:7], v[242:245], v[172:175], v[4:7]
	v_mfma_f32_16x16x32_bf16 v[32:35], v[212:215], v[152:155], v[32:35]
	v_mfma_f32_16x16x32_bf16 v[28:31], v[246:249], v[152:155], v[28:31]
	v_mfma_f32_16x16x32_bf16 v[24:27], v[212:215], v[160:163], v[24:27]
	v_mfma_f32_16x16x32_bf16 v[20:23], v[246:249], v[160:163], v[20:23]
	v_mfma_f32_16x16x32_bf16 v[16:19], v[212:215], v[168:171], v[16:19]
	v_mfma_f32_16x16x32_bf16 v[12:15], v[246:249], v[168:171], v[12:15]
	v_mfma_f32_16x16x32_bf16 v[8:11], v[212:215], v[204:207], v[8:11]
	v_mfma_f32_16x16x32_bf16 v[4:7], v[246:249], v[204:207], v[4:7]
	s_add_i32 s23, 0, 0x18000
	v_add_u32_e32 v2, s23, v187
	s_barrier
	ds_read_b128 v[132:135], v2
	ds_read_b128 v[136:139], v2 offset:1024
	ds_read_b128 v[140:143], v2 offset:2048
	ds_read_b128 v[144:147], v2 offset:3072
	s_add_u32 s24, s46, 0x40000
	s_addc_u32 s25, s47, 0
	s_mov_b32 m0, s82
	v_lshl_add_u64 v[208:209], s[24:25], 0, v[0:1]
	ds_read_b128 v[148:151], v240 offset:32768
	ds_read_b128 v[152:155], v240 offset:33792
	ds_read_b128 v[156:159], v240 offset:34816
	ds_read_b128 v[160:163], v240 offset:35840
	ds_read_b128 v[164:167], v240 offset:36864
	ds_read_b128 v[168:171], v240 offset:37888
	ds_read_b128 v[172:175], v240 offset:38912
	ds_read_b128 v[204:207], v240 offset:39936
	global_load_lds_dwordx4 v[208:209], off
	v_lshl_add_u64 v[208:209], s[24:25], 0, v[178:179]
	s_mov_b32 m0, s83
	s_nop 0
	global_load_lds_dwordx4 v[208:209], off
	s_waitcnt lgkmcnt(8)
	s_barrier
	s_waitcnt lgkmcnt(0)
	s_waitcnt lgkmcnt(0)
	v_mfma_f32_16x16x32_bf16 v[128:131], v[132:135], v[148:151], v[128:131]
	v_mfma_f32_16x16x32_bf16 v[124:127], v[140:143], v[148:151], v[124:127]
	v_mfma_f32_16x16x32_bf16 v[120:123], v[132:135], v[156:159], v[120:123]
	v_mfma_f32_16x16x32_bf16 v[116:119], v[140:143], v[156:159], v[116:119]
	v_mfma_f32_16x16x32_bf16 v[112:115], v[132:135], v[164:167], v[112:115]
	v_mfma_f32_16x16x32_bf16 v[108:111], v[140:143], v[164:167], v[108:111]
	v_mfma_f32_16x16x32_bf16 v[104:107], v[132:135], v[172:175], v[104:107]
	v_mfma_f32_16x16x32_bf16 v[100:103], v[140:143], v[172:175], v[100:103]
	v_mfma_f32_16x16x32_bf16 v[128:131], v[136:139], v[152:155], v[128:131]
	v_mfma_f32_16x16x32_bf16 v[124:127], v[144:147], v[152:155], v[124:127]
	v_mfma_f32_16x16x32_bf16 v[120:123], v[136:139], v[160:163], v[120:123]
	v_mfma_f32_16x16x32_bf16 v[116:119], v[144:147], v[160:163], v[116:119]
	v_mfma_f32_16x16x32_bf16 v[112:115], v[136:139], v[168:171], v[112:115]
	v_mfma_f32_16x16x32_bf16 v[108:111], v[144:147], v[168:171], v[108:111]
	v_mfma_f32_16x16x32_bf16 v[104:107], v[136:139], v[204:207], v[104:107]
	v_mfma_f32_16x16x32_bf16 v[100:103], v[144:147], v[204:207], v[100:103]
	s_barrier
	s_add_i32 s26, 0, 0x1c000
	s_add_i32 s23, s23, s67
	v_add_u32_e32 v2, s26, v187
	v_lshl_add_u64 v[250:251], v[250:251], 0, s[76:77]
	s_mov_b32 m0, s23
	ds_read_b128 v[208:211], v2
	ds_read_b128 v[212:215], v2 offset:1024
	ds_read_b128 v[242:245], v2 offset:2048
	ds_read_b128 v[246:249], v2 offset:3072
	global_load_lds_dwordx4 v[250:251], off
	v_lshl_add_u64 v[222:223], v[222:223], 0, s[76:77]
	s_add_i32 m0, s23, 0x2000
	s_nop 0
	global_load_lds_dwordx4 v[222:223], off
	s_barrier
	s_waitcnt lgkmcnt(0)
	s_waitcnt lgkmcnt(0)
	v_mfma_f32_16x16x32_bf16 v[64:67], v[208:211], v[148:151], v[64:67]
	v_mfma_f32_16x16x32_bf16 v[60:63], v[242:245], v[148:151], v[60:63]
	v_mfma_f32_16x16x32_bf16 v[56:59], v[208:211], v[156:159], v[56:59]
	v_mfma_f32_16x16x32_bf16 v[52:55], v[242:245], v[156:159], v[52:55]
	v_mfma_f32_16x16x32_bf16 v[48:51], v[208:211], v[164:167], v[48:51]
	v_mfma_f32_16x16x32_bf16 v[44:47], v[242:245], v[164:167], v[44:47]
	v_mfma_f32_16x16x32_bf16 v[40:43], v[208:211], v[172:175], v[40:43]
	v_mfma_f32_16x16x32_bf16 v[36:39], v[242:245], v[172:175], v[36:39]
	v_mfma_f32_16x16x32_bf16 v[64:67], v[212:215], v[152:155], v[64:67]
	v_mfma_f32_16x16x32_bf16 v[60:63], v[246:249], v[152:155], v[60:63]
	v_mfma_f32_16x16x32_bf16 v[56:59], v[212:215], v[160:163], v[56:59]
	v_mfma_f32_16x16x32_bf16 v[52:55], v[246:249], v[160:163], v[52:55]
	v_mfma_f32_16x16x32_bf16 v[48:51], v[212:215], v[168:171], v[48:51]
	v_mfma_f32_16x16x32_bf16 v[44:47], v[246:249], v[168:171], v[44:47]
	v_mfma_f32_16x16x32_bf16 v[40:43], v[212:215], v[204:207], v[40:43]
	v_mfma_f32_16x16x32_bf16 v[36:39], v[246:249], v[204:207], v[36:39]
	s_mov_b32 m0, s48
	v_lshl_add_u64 v[216:217], v[216:217], 0, s[76:77]
	s_barrier
	ds_read_b128 v[148:151], v240 offset:49152
	ds_read_b128 v[152:155], v240 offset:50176
	ds_read_b128 v[156:159], v240 offset:51200
	ds_read_b128 v[160:163], v240 offset:52224
	ds_read_b128 v[164:167], v240 offset:53248
	ds_read_b128 v[168:171], v240 offset:54272
	ds_read_b128 v[172:175], v240 offset:55296
	ds_read_b128 v[204:207], v240 offset:56320
	global_load_lds_dwordx4 v[216:217], off
	v_lshl_add_u64 v[216:217], v[236:237], 0, s[76:77]
	s_mov_b32 m0, s50
	s_nop 0
	global_load_lds_dwordx4 v[216:217], off
	s_barrier
	s_waitcnt lgkmcnt(0)
	s_waitcnt lgkmcnt(0)
	v_mfma_f32_16x16x32_bf16 v[96:99], v[132:135], v[148:151], v[96:99]
	v_mfma_f32_16x16x32_bf16 v[92:95], v[140:143], v[148:151], v[92:95]
	v_mfma_f32_16x16x32_bf16 v[88:91], v[132:135], v[156:159], v[88:91]
	v_mfma_f32_16x16x32_bf16 v[84:87], v[140:143], v[156:159], v[84:87]
	v_mfma_f32_16x16x32_bf16 v[80:83], v[132:135], v[164:167], v[80:83]
	v_mfma_f32_16x16x32_bf16 v[76:79], v[140:143], v[164:167], v[76:79]
	v_mfma_f32_16x16x32_bf16 v[72:75], v[132:135], v[172:175], v[72:75]
	v_mfma_f32_16x16x32_bf16 v[68:71], v[140:143], v[172:175], v[68:71]
	v_mfma_f32_16x16x32_bf16 v[96:99], v[136:139], v[152:155], v[96:99]
	v_mfma_f32_16x16x32_bf16 v[92:95], v[144:147], v[152:155], v[92:95]
	v_mfma_f32_16x16x32_bf16 v[88:91], v[136:139], v[160:163], v[88:91]
	v_mfma_f32_16x16x32_bf16 v[84:87], v[144:147], v[160:163], v[84:87]
	v_mfma_f32_16x16x32_bf16 v[80:83], v[136:139], v[168:171], v[80:83]
	v_mfma_f32_16x16x32_bf16 v[76:79], v[144:147], v[168:171], v[76:79]
	v_mfma_f32_16x16x32_bf16 v[72:75], v[136:139], v[204:207], v[72:75]
	v_mfma_f32_16x16x32_bf16 v[68:71], v[144:147], v[204:207], v[68:71]
	s_barrier
	s_add_u32 s24, s44, 0x40080
	s_addc_u32 s25, s45, 0
	s_add_i32 s23, s26, s67
	v_lshl_add_u64 v[132:133], s[24:25], 0, v[176:177]
	s_mov_b32 m0, s23
	s_nop 0
	global_load_lds_dwordx4 v[132:133], off
	v_lshl_add_u64 v[132:133], s[24:25], 0, v[180:181]
	s_add_i32 m0, s23, 0x2000
	s_nop 0
	global_load_lds_dwordx4 v[132:133], off
	s_waitcnt vmcnt(6)
	s_barrier
	v_mfma_f32_16x16x32_bf16 v[32:35], v[208:211], v[148:151], v[32:35]
	v_mfma_f32_16x16x32_bf16 v[28:31], v[242:245], v[148:151], v[28:31]
	v_mfma_f32_16x16x32_bf16 v[24:27], v[208:211], v[156:159], v[24:27]
	v_mfma_f32_16x16x32_bf16 v[20:23], v[242:245], v[156:159], v[20:23]
	v_mfma_f32_16x16x32_bf16 v[16:19], v[208:211], v[164:167], v[16:19]
	v_mfma_f32_16x16x32_bf16 v[12:15], v[242:245], v[164:167], v[12:15]
	v_mfma_f32_16x16x32_bf16 v[8:11], v[208:211], v[172:175], v[8:11]
	v_mfma_f32_16x16x32_bf16 v[4:7], v[242:245], v[172:175], v[4:7]
	v_mfma_f32_16x16x32_bf16 v[32:35], v[212:215], v[152:155], v[32:35]
	v_mfma_f32_16x16x32_bf16 v[28:31], v[246:249], v[152:155], v[28:31]
	v_mfma_f32_16x16x32_bf16 v[24:27], v[212:215], v[160:163], v[24:27]
	v_mfma_f32_16x16x32_bf16 v[20:23], v[246:249], v[160:163], v[20:23]
	v_mfma_f32_16x16x32_bf16 v[16:19], v[212:215], v[168:171], v[16:19]
	v_mfma_f32_16x16x32_bf16 v[12:15], v[246:249], v[168:171], v[12:15]
	v_mfma_f32_16x16x32_bf16 v[8:11], v[212:215], v[204:207], v[8:11]
	v_mfma_f32_16x16x32_bf16 v[4:7], v[246:249], v[204:207], v[4:7]
	s_add_i32 s22, s22, 2
	s_add_u32 s0, s0, 0x100
	s_addc_u32 s1, s1, 0
	s_add_u32 s20, s20, 0x100
	s_addc_u32 s21, s21, 0
	s_cmp_gt_u32 s22, 13
	s_barrier
	s_cbranch_scc0 .LBB0_427
	s_add_i32 s0, s61, -8
	s_cmp_lt_u32 s0, 12
	s_mov_b64 s[0:1], -1
	s_cbranch_scc1 .LBB0_451
	s_cmp_gt_i32 s61, 33
	s_cselect_b64 s[64:65], -1, 0
	s_lshl_b32 s0, s61, 8
	s_lshl_b32 s53, s60, 8
	s_add_i32 s1, s0, 0xffffee00
	s_cmp_lt_i32 s61, 26
	v_cndmask_b32_e64 v2, 0, 1, s[36:37]
	s_cselect_b32 s62, s0, s1
	s_mov_b64 s[0:1], -1
	s_and_b64 vcc, exec, s[64:65]
	v_cmp_ne_u32_e64 s[44:45], 1, v2
	s_cbranch_vccz .LBB0_433
	s_and_b64 vcc, exec, s[44:45]
	s_cbranch_vccnz .LBB0_432
	v_add_u32_e32 v132, s53, v185
	v_ashrrev_i32_e32 v133, 31, v132
	v_lshlrev_b64 v[140:141], 7, v[132:133]
	global_load_dwordx4 v[204:207], v[188:189], off offset:16
	global_load_dwordx4 v[208:211], v[188:189], off
	s_mov_b32 s3, 0xbfb8aa3b
	s_mov_b32 s2, 0x800000
	s_mov_b32 s4, 0x3f317217
	s_mov_b32 s5, 0x7f800000
	s_waitcnt vmcnt(0)
	v_mov_b32_e32 v132, v204
	v_mov_b32_e32 v133, v205
	v_mov_b32_e32 v134, v206
	v_mov_b32_e32 v135, v207
	v_mov_b32_e32 v136, v208
	v_mov_b32_e32 v137, v209
	v_mov_b32_e32 v138, v210
	v_mov_b32_e32 v139, v211
	v_add_f32_e32 v147, v126, v134
	v_add_f32_e32 v2, v128, v136
	v_max_f32_e32 v142, 0, v2
	v_mul_f32_e64 v2, |v2|, s3
	v_exp_f32_e32 v2, v2
	v_add_f32_e32 v136, v124, v132
	v_add_f32_e32 v149, v127, v135
	v_add_f32_e32 v2, 1.0, v2
	v_cmp_gt_f32_e32 vcc, s2, v2
	s_nop 1
	v_cndmask_b32_e64 v132, 0, 32, vcc
	v_ldexp_f32 v2, v2, v132
	v_log_f32_e32 v2, v2
	s_nop 0
	v_mul_f32_e32 v132, 0x3f317217, v2
	v_fma_f32 v132, v2, s4, -v132
	v_fmac_f32_e32 v132, 0x3377d1cf, v2
	v_fmac_f32_e32 v132, 0x3f317217, v2
	v_cmp_lt_f32_e64 s[0:1], |v2|, s5
	s_nop 1
	v_cndmask_b32_e64 v2, v2, v132, s[0:1]
	v_cndmask_b32_e32 v132, 0, v228, vcc
	v_sub_f32_e32 v144, v2, v132
	v_mul_f32_e64 v2, |v136|, s3
	v_exp_f32_e32 v2, v2
	v_max_f32_e32 v132, 0, v136
	v_add_f32_e32 v2, 1.0, v2
	v_cmp_gt_f32_e32 vcc, s2, v2
	s_nop 1
	v_cndmask_b32_e64 v136, 0, 32, vcc
	v_ldexp_f32 v2, v2, v136
	v_log_f32_e32 v2, v2
	s_nop 0
	v_mul_f32_e32 v136, 0x3f317217, v2
	v_fma_f32 v136, v2, s4, -v136
	v_fmac_f32_e32 v136, 0x3377d1cf, v2
	v_fmac_f32_e32 v136, 0x3f317217, v2
	v_cmp_lt_f32_e64 s[0:1], |v2|, s5
	s_nop 1
	v_cndmask_b32_e64 v2, v2, v136, s[0:1]
	v_cndmask_b32_e32 v136, 0, v228, vcc
	v_sub_f32_e32 v136, v2, v136
	v_add_f32_e32 v2, v129, v137
	v_max_f32_e32 v143, 0, v2
	v_mul_f32_e64 v2, |v2|, s3
	v_exp_f32_e32 v2, v2
	v_add_f32_e32 v137, v125, v133
	v_add_f32_e32 v2, 1.0, v2
	v_cmp_gt_f32_e32 vcc, s2, v2
	s_nop 1
	v_cndmask_b32_e64 v133, 0, 32, vcc
	v_ldexp_f32 v2, v2, v133
	v_log_f32_e32 v2, v2
	s_nop 0
	v_mul_f32_e32 v133, 0x3f317217, v2
	v_fma_f32 v133, v2, s4, -v133
	v_fmac_f32_e32 v133, 0x3377d1cf, v2
	v_fmac_f32_e32 v133, 0x3f317217, v2
	v_cmp_lt_f32_e64 s[0:1], |v2|, s5
	s_nop 1
	v_cndmask_b32_e64 v2, v2, v133, s[0:1]
	v_cndmask_b32_e32 v133, 0, v228, vcc
	v_sub_f32_e32 v145, v2, v133
	v_mul_f32_e64 v2, |v137|, s3
	v_exp_f32_e32 v2, v2
	v_max_f32_e32 v133, 0, v137
	v_pk_add_f32 v[142:143], v[142:143], v[144:145]
	v_add_f32_e32 v2, 1.0, v2
	v_cmp_gt_f32_e32 vcc, s2, v2
	s_nop 1
	v_cndmask_b32_e64 v137, 0, 32, vcc
	v_ldexp_f32 v2, v2, v137
	v_log_f32_e32 v2, v2
	s_nop 0
	v_mul_f32_e32 v137, 0x3f317217, v2
	v_fma_f32 v137, v2, s4, -v137
	v_fmac_f32_e32 v137, 0x3377d1cf, v2
	v_fmac_f32_e32 v137, 0x3f317217, v2
	v_cmp_lt_f32_e64 s[0:1], |v2|, s5
	s_nop 1
	v_cndmask_b32_e64 v2, v2, v137, s[0:1]
	v_cndmask_b32_e32 v137, 0, v228, vcc
	v_sub_f32_e32 v137, v2, v137
	v_add_f32_e32 v2, v130, v138
	v_max_f32_e32 v138, 0, v2
	v_mul_f32_e64 v2, |v2|, s3
	v_exp_f32_e32 v2, v2
	v_pk_add_f32 v[132:133], v[132:133], v[136:137]
	v_lshl_add_u64 v[136:137], v[190:191], 0, v[140:141]
	v_add_f32_e32 v2, 1.0, v2
	v_cmp_gt_f32_e32 vcc, s2, v2
	s_nop 1
	v_cndmask_b32_e64 v134, 0, 32, vcc
	v_ldexp_f32 v2, v2, v134
	v_log_f32_e32 v2, v2
	s_nop 0
	v_mul_f32_e32 v134, 0x3f317217, v2
	v_fma_f32 v134, v2, s4, -v134
	v_fmac_f32_e32 v134, 0x3377d1cf, v2
	v_fmac_f32_e32 v134, 0x3f317217, v2
	v_cmp_lt_f32_e64 s[0:1], |v2|, s5
	s_nop 1
	v_cndmask_b32_e64 v2, v2, v134, s[0:1]
	v_cndmask_b32_e32 v134, 0, v228, vcc
	v_sub_f32_e32 v146, v2, v134
	v_mul_f32_e64 v2, |v147|, s3
	v_exp_f32_e32 v2, v2
	v_max_f32_e32 v134, 0, v147
	v_add_f32_e32 v2, 1.0, v2
	v_cmp_gt_f32_e32 vcc, s2, v2
	s_nop 1
	v_cndmask_b32_e64 v147, 0, 32, vcc
	v_ldexp_f32 v2, v2, v147
	v_log_f32_e32 v2, v2
	s_nop 0
	v_mul_f32_e32 v147, 0x3f317217, v2
	v_fma_f32 v147, v2, s4, -v147
	v_fmac_f32_e32 v147, 0x3377d1cf, v2
	v_fmac_f32_e32 v147, 0x3f317217, v2
	v_cmp_lt_f32_e64 s[0:1], |v2|, s5
	s_nop 1
	v_cndmask_b32_e64 v2, v2, v147, s[0:1]
	v_cndmask_b32_e32 v147, 0, v228, vcc
	v_sub_f32_e32 v148, v2, v147
	v_add_f32_e32 v2, v131, v139
	v_max_f32_e32 v139, 0, v2
	v_mul_f32_e64 v2, |v2|, s3
	v_exp_f32_e32 v2, v2
	s_nop 0
	v_add_f32_e32 v2, 1.0, v2
	v_cmp_gt_f32_e32 vcc, s2, v2
	s_nop 1
	v_cndmask_b32_e64 v135, 0, 32, vcc
	v_ldexp_f32 v2, v2, v135
	v_log_f32_e32 v2, v2
	s_nop 0
	v_mul_f32_e32 v135, 0x3f317217, v2
	v_fma_f32 v135, v2, s4, -v135
	v_fmac_f32_e32 v135, 0x3377d1cf, v2
	v_fmac_f32_e32 v135, 0x3f317217, v2
	v_cmp_lt_f32_e64 s[0:1], |v2|, s5
	s_nop 1
	v_cndmask_b32_e64 v2, v2, v135, s[0:1]
	v_cndmask_b32_e32 v135, 0, v228, vcc
	v_sub_f32_e32 v147, v2, v135
	v_mul_f32_e64 v2, |v149|, s3
	v_exp_f32_e32 v2, v2
	v_pk_add_f32 v[144:145], v[138:139], v[146:147]
	v_max_f32_e32 v135, 0, v149
	v_add_f32_e32 v2, 1.0, v2
	v_cmp_gt_f32_e32 vcc, s2, v2
	s_nop 1
	v_cndmask_b32_e64 v138, 0, 32, vcc
	v_ldexp_f32 v2, v2, v138
	v_log_f32_e32 v2, v2
	s_nop 0
	v_mul_f32_e32 v138, 0x3f317217, v2
	v_fma_f32 v138, v2, s4, -v138
	v_fmac_f32_e32 v138, 0x3377d1cf, v2
	v_fmac_f32_e32 v138, 0x3f317217, v2
	v_cmp_lt_f32_e64 s[0:1], |v2|, s5
	s_nop 1
	v_cndmask_b32_e64 v2, v2, v138, s[0:1]
	v_cndmask_b32_e32 v138, 0, v228, vcc
	v_sub_f32_e32 v149, v2, v138
	v_pk_add_f32 v[134:135], v[134:135], v[148:149]
	global_store_dwordx4 v[136:137], v[142:145], off
	global_store_dwordx4 v[136:137], v[132:135], off offset:16
